# K-loops: first iteration peeled with C=0 on each accumulator's first MFMA; the 128 accumulator-zeroing v_mov per tile removed
# speedup vs baseline: 1.0175x; 1.0051x over previous
.LBB0_438:
	s_ashr_i32 s57, s56, 31
	s_lshl_b64 s[58:59], s[56:57], 19
	s_add_u32 s58, s0, s58
	s_addc_u32 s59, s1, s59
	s_and_b64 s[60:61], s[10:11], exec
	s_cselect_b32 s53, s59, s65
	s_cselect_b32 s57, s58, s64
	s_ashr_i32 s55, s54, 31
	s_lshl_b64 s[60:61], s[54:55], 19
	s_add_u32 s60, s3, s60
	s_addc_u32 s61, s22, s61
	s_and_b64 s[68:69], s[10:11], exec
	s_cselect_b32 s55, s61, s67
	s_cselect_b32 s63, s60, s66
	s_add_u32 s64, s64, 0x40080
	s_addc_u32 s65, s65, 0
	s_add_u32 s84, s66, 0x100
	s_addc_u32 s85, s67, 0
	s_mov_b32 s86, -2
	ds_read_b128 v[128:131], v192
	ds_read_b128 v[132:135], v192 offset:1024
	ds_read_b128 v[136:139], v192 offset:2048
	ds_read_b128 v[158:161], v192 offset:3072
	ds_read_b128 v[168:171], v193
	ds_read_b128 v[172:175], v193 offset:1024
	ds_read_b128 v[196:199], v193 offset:2048
	ds_read_b128 v[200:203], v193 offset:3072
	s_add_u32 s66, s64, 0xfffc0080
	s_addc_u32 s67, s65, -1
	s_cmp_eq_u32 s86, 12
	s_cselect_b32 s69, s53, s67
	s_cselect_b32 s68, s57, s66
	s_cselect_b32 s67, s55, s85
	s_cselect_b32 s66, s63, s84
	s_cselect_b32 s98, 1, 0
	s_add_i32 m0, s70, 0xc000
	ds_read_b128 v[204:207], v194
	ds_read_b128 v[208:211], v194 offset:1024
	ds_read_b128 v[212:215], v194 offset:2048
	ds_read_b128 v[216:219], v194 offset:3072
	ds_read_b128 v[220:223], v194 offset:4096
	ds_read_b128 v[224:227], v194 offset:5120
	ds_read_b128 v[228:231], v194 offset:6144
	ds_read_b128 v[232:235], v194 offset:7168
	global_load_lds_dwordx4 v150, s[64:65]
	s_add_i32 m0, s70, 0xe000
	s_nop 0
	global_load_lds_dwordx4 v152, s[64:65]
	s_waitcnt vmcnt(8)
	s_waitcnt lgkmcnt(0)
	s_setprio 1
	s_cmp_lg_u32 s98, 0
	s_cbranch_scc0 .Lg1_nopf_pk
	s_lshl_b32 s99, s52, 8
	v_add_u32_e32 v240, s99, v165
	v_ashrrev_i32_e32 v241, 31, v240
	v_lshl_add_u64 v[240:241], v[240:241], 2, s[20:21]
	global_load_dword v242, v[240:241], off
	global_load_dword v243, v[240:241], off offset:64
	global_load_dword v244, v[240:241], off offset:128
	global_load_dword v245, v[240:241], off offset:192
	global_load_dword v246, v[240:241], off offset:512
	global_load_dword v248, v[240:241], off offset:576
	global_load_dword v249, v[240:241], off offset:640
	global_load_dword v250, v[240:241], off offset:704
.Lg1_nopf_pk:
	s_barrier
	v_mfma_f32_16x16x32_bf16 v[124:127], v[128:131], v[204:207], 0
	v_mfma_f32_16x16x32_bf16 v[120:123], v[136:139], v[204:207], 0
	v_mfma_f32_16x16x32_bf16 v[96:99], v[128:131], v[212:215], 0
	v_mfma_f32_16x16x32_bf16 v[88:91], v[136:139], v[212:215], 0
	v_mfma_f32_16x16x32_bf16 v[76:79], v[128:131], v[220:223], 0
	v_mfma_f32_16x16x32_bf16 v[72:75], v[136:139], v[220:223], 0
	v_mfma_f32_16x16x32_bf16 v[60:63], v[128:131], v[228:231], 0
	v_mfma_f32_16x16x32_bf16 v[108:111], v[136:139], v[228:231], 0
	v_mfma_f32_16x16x32_bf16 v[124:127], v[132:135], v[208:211], v[124:127]
	v_mfma_f32_16x16x32_bf16 v[120:123], v[158:161], v[208:211], v[120:123]
	v_mfma_f32_16x16x32_bf16 v[96:99], v[132:135], v[216:219], v[96:99]
	v_mfma_f32_16x16x32_bf16 v[88:91], v[158:161], v[216:219], v[88:91]
	v_mfma_f32_16x16x32_bf16 v[76:79], v[132:135], v[224:227], v[76:79]
	v_mfma_f32_16x16x32_bf16 v[72:75], v[158:161], v[224:227], v[72:75]
	v_mfma_f32_16x16x32_bf16 v[60:63], v[132:135], v[232:235], v[60:63]
	v_mfma_f32_16x16x32_bf16 v[108:111], v[158:161], v[232:235], v[108:111]
	v_mfma_f32_16x16x32_bf16 v[116:119], v[168:171], v[204:207], 0
	v_mfma_f32_16x16x32_bf16 v[112:115], v[196:199], v[204:207], 0
	v_mfma_f32_16x16x32_bf16 v[84:87], v[168:171], v[212:215], 0
	v_mfma_f32_16x16x32_bf16 v[80:83], v[196:199], v[212:215], 0
	v_mfma_f32_16x16x32_bf16 v[68:71], v[168:171], v[220:223], 0
	v_mfma_f32_16x16x32_bf16 v[64:67], v[196:199], v[220:223], 0
	v_mfma_f32_16x16x32_bf16 v[104:107], v[168:171], v[228:231], 0
	v_mfma_f32_16x16x32_bf16 v[56:59], v[196:199], v[228:231], 0
	v_mfma_f32_16x16x32_bf16 v[116:119], v[172:175], v[208:211], v[116:119]
	v_mfma_f32_16x16x32_bf16 v[112:115], v[200:203], v[208:211], v[112:115]
	v_mfma_f32_16x16x32_bf16 v[84:87], v[172:175], v[216:219], v[84:87]
	v_mfma_f32_16x16x32_bf16 v[80:83], v[200:203], v[216:219], v[80:83]
	v_mfma_f32_16x16x32_bf16 v[68:71], v[172:175], v[224:227], v[68:71]
	v_mfma_f32_16x16x32_bf16 v[64:67], v[200:203], v[224:227], v[64:67]
	v_mfma_f32_16x16x32_bf16 v[104:107], v[172:175], v[232:235], v[104:107]
	v_mfma_f32_16x16x32_bf16 v[56:59], v[200:203], v[232:235], v[56:59]
	s_barrier
	s_setprio 0
	s_add_i32 s87, s82, s23
	s_add_u32 s98, s66, 0x80
	s_addc_u32 s99, s67, 0
	s_mov_b32 m0, s87
	ds_read_b128 v[204:207], v194 offset:16384
	ds_read_b128 v[208:211], v194 offset:17408
	ds_read_b128 v[212:215], v194 offset:18432
	ds_read_b128 v[216:219], v194 offset:19456
	ds_read_b128 v[220:223], v194 offset:20480
	ds_read_b128 v[224:227], v194 offset:21504
	ds_read_b128 v[228:231], v194 offset:22528
	ds_read_b128 v[232:235], v194 offset:23552
	global_load_lds_dwordx4 v140, s[66:67]
	s_add_i32 m0, s87, 0x2000
	s_add_u32 s88, s66, 0x40000
	s_addc_u32 s89, s67, 0
	s_add_i32 s87, s83, s23
	global_load_lds_dwordx4 v142, s[66:67]
	s_mov_b32 m0, s87
	s_add_u32 s100, s68, 0x80
	s_addc_u32 s101, s69, 0
	global_load_lds_dwordx4 v140, s[88:89]
	s_add_i32 m0, s87, 0x2000
	s_nop 0
	global_load_lds_dwordx4 v142, s[88:89]
	s_mov_b32 m0, s70
	s_nop 0
	global_load_lds_dwordx4 v140, s[68:69]
	s_mov_b32 m0, s71
	s_nop 0
	global_load_lds_dwordx4 v142, s[68:69]
	s_waitcnt vmcnt(8)
	s_waitcnt lgkmcnt(0)
	s_setprio 1
	s_barrier
	v_mfma_f32_16x16x32_bf16 v[52:55], v[128:131], v[204:207], 0
	v_mfma_f32_16x16x32_bf16 v[48:51], v[136:139], v[204:207], 0
	v_mfma_f32_16x16x32_bf16 v[16:19], v[128:131], v[212:215], 0
	v_mfma_f32_16x16x32_bf16 v[8:11], v[136:139], v[212:215], 0
	v_mfma_f32_16x16x32_bf16 v[28:31], v[128:131], v[220:223], 0
	v_mfma_f32_16x16x32_bf16 v[24:27], v[136:139], v[220:223], 0
	v_mfma_f32_16x16x32_bf16 v[36:39], v[128:131], v[228:231], 0
	v_mfma_f32_16x16x32_bf16 v[100:103], v[136:139], v[228:231], 0
	v_mfma_f32_16x16x32_bf16 v[52:55], v[132:135], v[208:211], v[52:55]
	v_mfma_f32_16x16x32_bf16 v[48:51], v[158:161], v[208:211], v[48:51]
	v_mfma_f32_16x16x32_bf16 v[16:19], v[132:135], v[216:219], v[16:19]
	v_mfma_f32_16x16x32_bf16 v[8:11], v[158:161], v[216:219], v[8:11]
	v_mfma_f32_16x16x32_bf16 v[28:31], v[132:135], v[224:227], v[28:31]
	v_mfma_f32_16x16x32_bf16 v[24:27], v[158:161], v[224:227], v[24:27]
	v_mfma_f32_16x16x32_bf16 v[36:39], v[132:135], v[232:235], v[36:39]
	v_mfma_f32_16x16x32_bf16 v[100:103], v[158:161], v[232:235], v[100:103]
	v_mfma_f32_16x16x32_bf16 v[44:47], v[168:171], v[204:207], 0
	v_mfma_f32_16x16x32_bf16 v[40:43], v[196:199], v[204:207], 0
	v_mfma_f32_16x16x32_bf16 v[0:3], v[168:171], v[212:215], 0
	v_mfma_f32_16x16x32_bf16 v[4:7], v[196:199], v[212:215], 0
	v_mfma_f32_16x16x32_bf16 v[12:15], v[168:171], v[220:223], 0
	v_mfma_f32_16x16x32_bf16 v[20:23], v[196:199], v[220:223], 0
	v_mfma_f32_16x16x32_bf16 v[92:95], v[168:171], v[228:231], 0
	v_mfma_f32_16x16x32_bf16 v[32:35], v[196:199], v[228:231], 0
	v_mfma_f32_16x16x32_bf16 v[44:47], v[172:175], v[208:211], v[44:47]
	v_mfma_f32_16x16x32_bf16 v[40:43], v[200:203], v[208:211], v[40:43]
	v_mfma_f32_16x16x32_bf16 v[0:3], v[172:175], v[216:219], v[0:3]
	v_mfma_f32_16x16x32_bf16 v[4:7], v[200:203], v[216:219], v[4:7]
	v_mfma_f32_16x16x32_bf16 v[12:15], v[172:175], v[224:227], v[12:15]
	v_mfma_f32_16x16x32_bf16 v[20:23], v[200:203], v[224:227], v[20:23]
	v_mfma_f32_16x16x32_bf16 v[92:95], v[172:175], v[232:235], v[92:95]
	v_mfma_f32_16x16x32_bf16 v[32:35], v[200:203], v[232:235], v[32:35]
	s_barrier
	s_setprio 0
	s_add_i32 s87, 0, 0x18000
	s_add_i32 s88, 0, 0x1c000
	v_add_u32_e32 v158, s87, v167
	v_add_u32_e32 v164, s88, v167
	ds_read_b128 v[128:131], v158
	ds_read_b128 v[132:135], v158 offset:1024
	ds_read_b128 v[136:139], v158 offset:2048
	ds_read_b128 v[158:161], v158 offset:3072
	ds_read_b128 v[168:171], v164
	ds_read_b128 v[172:175], v164 offset:1024
	ds_read_b128 v[196:199], v164 offset:2048
	ds_read_b128 v[200:203], v164 offset:3072
	s_add_u32 s68, s68, 0x40000
	s_addc_u32 s69, s69, 0
	s_mov_b32 m0, s72
	ds_read_b128 v[204:207], v194 offset:32768
	ds_read_b128 v[208:211], v194 offset:33792
	ds_read_b128 v[212:215], v194 offset:34816
	ds_read_b128 v[216:219], v194 offset:35840
	ds_read_b128 v[220:223], v194 offset:36864
	ds_read_b128 v[224:227], v194 offset:37888
	ds_read_b128 v[228:231], v194 offset:38912
	ds_read_b128 v[232:235], v194 offset:39936
	global_load_lds_dwordx4 v140, s[68:69]
	s_mov_b32 m0, s73
	s_nop 0
	global_load_lds_dwordx4 v142, s[68:69]
	s_waitcnt vmcnt(8)
	s_waitcnt lgkmcnt(0)
	s_setprio 1
	s_barrier
	v_mfma_f32_16x16x32_bf16 v[124:127], v[128:131], v[204:207], v[124:127]
	v_mfma_f32_16x16x32_bf16 v[120:123], v[136:139], v[204:207], v[120:123]
	v_mfma_f32_16x16x32_bf16 v[96:99], v[128:131], v[212:215], v[96:99]
	v_mfma_f32_16x16x32_bf16 v[88:91], v[136:139], v[212:215], v[88:91]
	v_mfma_f32_16x16x32_bf16 v[76:79], v[128:131], v[220:223], v[76:79]
	v_mfma_f32_16x16x32_bf16 v[72:75], v[136:139], v[220:223], v[72:75]
	v_mfma_f32_16x16x32_bf16 v[60:63], v[128:131], v[228:231], v[60:63]
	v_mfma_f32_16x16x32_bf16 v[108:111], v[136:139], v[228:231], v[108:111]
	v_mfma_f32_16x16x32_bf16 v[124:127], v[132:135], v[208:211], v[124:127]
	v_mfma_f32_16x16x32_bf16 v[120:123], v[158:161], v[208:211], v[120:123]
	v_mfma_f32_16x16x32_bf16 v[96:99], v[132:135], v[216:219], v[96:99]
	v_mfma_f32_16x16x32_bf16 v[88:91], v[158:161], v[216:219], v[88:91]
	v_mfma_f32_16x16x32_bf16 v[76:79], v[132:135], v[224:227], v[76:79]
	v_mfma_f32_16x16x32_bf16 v[72:75], v[158:161], v[224:227], v[72:75]
	v_mfma_f32_16x16x32_bf16 v[60:63], v[132:135], v[232:235], v[60:63]
	v_mfma_f32_16x16x32_bf16 v[108:111], v[158:161], v[232:235], v[108:111]
	v_mfma_f32_16x16x32_bf16 v[116:119], v[168:171], v[204:207], v[116:119]
	v_mfma_f32_16x16x32_bf16 v[112:115], v[196:199], v[204:207], v[112:115]
	v_mfma_f32_16x16x32_bf16 v[84:87], v[168:171], v[212:215], v[84:87]
	v_mfma_f32_16x16x32_bf16 v[80:83], v[196:199], v[212:215], v[80:83]
	v_mfma_f32_16x16x32_bf16 v[68:71], v[168:171], v[220:223], v[68:71]
	v_mfma_f32_16x16x32_bf16 v[64:67], v[196:199], v[220:223], v[64:67]
	v_mfma_f32_16x16x32_bf16 v[104:107], v[168:171], v[228:231], v[104:107]
	v_mfma_f32_16x16x32_bf16 v[56:59], v[196:199], v[228:231], v[56:59]
	v_mfma_f32_16x16x32_bf16 v[116:119], v[172:175], v[208:211], v[116:119]
	v_mfma_f32_16x16x32_bf16 v[112:115], v[200:203], v[208:211], v[112:115]
	v_mfma_f32_16x16x32_bf16 v[84:87], v[172:175], v[216:219], v[84:87]
	v_mfma_f32_16x16x32_bf16 v[80:83], v[200:203], v[216:219], v[80:83]
	v_mfma_f32_16x16x32_bf16 v[68:71], v[172:175], v[224:227], v[68:71]
	v_mfma_f32_16x16x32_bf16 v[64:67], v[200:203], v[224:227], v[64:67]
	v_mfma_f32_16x16x32_bf16 v[104:107], v[172:175], v[232:235], v[104:107]
	v_mfma_f32_16x16x32_bf16 v[56:59], v[200:203], v[232:235], v[56:59]
	s_barrier
	s_setprio 0
	s_add_i32 s68, s87, s23
	s_mov_b32 m0, s68
	ds_read_b128 v[204:207], v194 offset:49152
	ds_read_b128 v[208:211], v194 offset:50176
	ds_read_b128 v[212:215], v194 offset:51200
	ds_read_b128 v[216:219], v194 offset:52224
	ds_read_b128 v[220:223], v194 offset:53248
	ds_read_b128 v[224:227], v194 offset:54272
	ds_read_b128 v[228:231], v194 offset:55296
	ds_read_b128 v[232:235], v194 offset:56320
	global_load_lds_dwordx4 v140, s[98:99]
	s_add_i32 m0, s68, 0x2000
	s_add_u32 s66, s66, 0x40080
	s_addc_u32 s67, s67, 0
	s_add_i32 s68, s88, s23
	global_load_lds_dwordx4 v142, s[98:99]
	s_mov_b32 m0, s68
	s_nop 0
	global_load_lds_dwordx4 v140, s[66:67]
	s_add_i32 m0, s68, 0x2000
	s_nop 0
	global_load_lds_dwordx4 v142, s[66:67]
	s_mov_b32 m0, s80
	s_nop 0
	global_load_lds_dwordx4 v140, s[100:101]
	s_mov_b32 m0, s81
	s_nop 0
	global_load_lds_dwordx4 v142, s[100:101]
	s_waitcnt vmcnt(8)
	s_waitcnt lgkmcnt(0)
	s_setprio 1
	s_barrier
	v_mfma_f32_16x16x32_bf16 v[52:55], v[128:131], v[204:207], v[52:55]
	v_mfma_f32_16x16x32_bf16 v[48:51], v[136:139], v[204:207], v[48:51]
	v_mfma_f32_16x16x32_bf16 v[16:19], v[128:131], v[212:215], v[16:19]
	v_mfma_f32_16x16x32_bf16 v[8:11], v[136:139], v[212:215], v[8:11]
	v_mfma_f32_16x16x32_bf16 v[28:31], v[128:131], v[220:223], v[28:31]
	v_mfma_f32_16x16x32_bf16 v[24:27], v[136:139], v[220:223], v[24:27]
	v_mfma_f32_16x16x32_bf16 v[36:39], v[128:131], v[228:231], v[36:39]
	v_mfma_f32_16x16x32_bf16 v[100:103], v[136:139], v[228:231], v[100:103]
	v_mfma_f32_16x16x32_bf16 v[52:55], v[132:135], v[208:211], v[52:55]
	v_mfma_f32_16x16x32_bf16 v[48:51], v[158:161], v[208:211], v[48:51]
	v_mfma_f32_16x16x32_bf16 v[16:19], v[132:135], v[216:219], v[16:19]
	v_mfma_f32_16x16x32_bf16 v[8:11], v[158:161], v[216:219], v[8:11]
	v_mfma_f32_16x16x32_bf16 v[28:31], v[132:135], v[224:227], v[28:31]
	v_mfma_f32_16x16x32_bf16 v[24:27], v[158:161], v[224:227], v[24:27]
	v_mfma_f32_16x16x32_bf16 v[36:39], v[132:135], v[232:235], v[36:39]
	v_mfma_f32_16x16x32_bf16 v[100:103], v[158:161], v[232:235], v[100:103]
	v_mfma_f32_16x16x32_bf16 v[44:47], v[168:171], v[204:207], v[44:47]
	v_mfma_f32_16x16x32_bf16 v[40:43], v[196:199], v[204:207], v[40:43]
	v_mfma_f32_16x16x32_bf16 v[0:3], v[168:171], v[212:215], v[0:3]
	v_mfma_f32_16x16x32_bf16 v[4:7], v[196:199], v[212:215], v[4:7]
	v_mfma_f32_16x16x32_bf16 v[12:15], v[168:171], v[220:223], v[12:15]
	v_mfma_f32_16x16x32_bf16 v[20:23], v[196:199], v[220:223], v[20:23]
	v_mfma_f32_16x16x32_bf16 v[92:95], v[168:171], v[228:231], v[92:95]
	v_mfma_f32_16x16x32_bf16 v[32:35], v[196:199], v[228:231], v[32:35]
	v_mfma_f32_16x16x32_bf16 v[44:47], v[172:175], v[208:211], v[44:47]
	v_mfma_f32_16x16x32_bf16 v[40:43], v[200:203], v[208:211], v[40:43]
	v_mfma_f32_16x16x32_bf16 v[0:3], v[172:175], v[216:219], v[0:3]
	v_mfma_f32_16x16x32_bf16 v[4:7], v[200:203], v[216:219], v[4:7]
	v_mfma_f32_16x16x32_bf16 v[12:15], v[172:175], v[224:227], v[12:15]
	v_mfma_f32_16x16x32_bf16 v[20:23], v[200:203], v[224:227], v[20:23]
	v_mfma_f32_16x16x32_bf16 v[92:95], v[172:175], v[232:235], v[92:95]
	v_mfma_f32_16x16x32_bf16 v[32:35], v[200:203], v[232:235], v[32:35]
	s_barrier
	s_setprio 0
	s_add_i32 s86, s86, 2
	s_add_u32 s64, s64, 0x100
	s_addc_u32 s65, s65, 0
	s_add_u32 s84, s84, 0x100
	s_addc_u32 s85, s85, 0
	s_cmp_gt_u32 s86, 13
	s_cbranch_scc1 .Lkx_439

.Lkx_439:
	s_and_b64 vcc, exec, s[38:39]
	s_cbranch_vccz .LBB0_442
	s_barrier

.LBB0_503:
	s_ashr_i32 s39, s38, 31
	s_lshl_b64 s[40:41], s[38:39], 19
	s_add_u32 s40, s0, s40
	s_addc_u32 s41, s1, s41
	s_and_b64 s[42:43], s[6:7], exec
	s_cselect_b32 s39, s41, s47
	s_cselect_b32 s45, s40, s46
	s_ashr_i32 s37, s36, 31
	s_lshl_b64 s[42:43], s[36:37], 19
	s_add_u32 s42, s22, s42
	s_addc_u32 s43, s23, s43
	s_and_b64 s[50:51], s[6:7], exec
	s_cselect_b32 s37, s43, s49
	s_cselect_b32 s84, s42, s48
	s_add_u32 s46, s46, 0x40080
	s_addc_u32 s47, s47, 0
	s_add_u32 s85, s48, 0x100
	s_addc_u32 s86, s49, 0
	s_mov_b32 s87, -2
	ds_read_b128 v[104:107], v200
	ds_read_b128 v[108:111], v200 offset:1024
	ds_read_b128 v[124:127], v200 offset:2048
	ds_read_b128 v[128:131], v200 offset:3072
	ds_read_b128 v[144:147], v201
	ds_read_b128 v[148:151], v201 offset:1024
	ds_read_b128 v[152:155], v201 offset:2048
	ds_read_b128 v[156:159], v201 offset:3072
	s_add_u32 s48, s46, 0xfffc0080
	s_addc_u32 s49, s47, -1
	s_cmp_eq_u32 s87, 12
	s_cselect_b32 s51, s39, s49
	s_cselect_b32 s50, s45, s48
	s_cselect_b32 s49, s37, s86
	s_cselect_b32 s48, s84, s85
	s_add_i32 m0, s52, 0xc000
	ds_read_b128 v[160:163], v202
	ds_read_b128 v[164:167], v202 offset:1024
	ds_read_b128 v[168:171], v202 offset:2048
	ds_read_b128 v[172:175], v202 offset:3072
	ds_read_b128 v[176:179], v202 offset:4096
	ds_read_b128 v[180:183], v202 offset:5120
	ds_read_b128 v[206:209], v202 offset:6144
	ds_read_b128 v[210:213], v202 offset:7168
	global_load_lds_dwordx4 v188, s[46:47]
	s_add_i32 m0, s52, 0xe000
	s_nop 0
	global_load_lds_dwordx4 v190, s[46:47]
	s_waitcnt vmcnt(8)
	s_waitcnt lgkmcnt(0)
	s_setprio 1
	s_barrier
	v_mfma_f32_16x16x32_bf16 v[140:143], v[104:107], v[160:163], 0
	v_mfma_f32_16x16x32_bf16 v[136:139], v[124:127], v[160:163], 0
	v_mfma_f32_16x16x32_bf16 v[116:119], v[104:107], v[168:171], 0
	v_mfma_f32_16x16x32_bf16 v[112:115], v[124:127], v[168:171], 0
	v_mfma_f32_16x16x32_bf16 v[92:95], v[104:107], v[176:179], 0
	v_mfma_f32_16x16x32_bf16 v[88:91], v[124:127], v[176:179], 0
	v_mfma_f32_16x16x32_bf16 v[76:79], v[104:107], v[206:209], 0
	v_mfma_f32_16x16x32_bf16 v[72:75], v[124:127], v[206:209], 0
	v_mfma_f32_16x16x32_bf16 v[140:143], v[108:111], v[164:167], v[140:143]
	v_mfma_f32_16x16x32_bf16 v[136:139], v[128:131], v[164:167], v[136:139]
	v_mfma_f32_16x16x32_bf16 v[116:119], v[108:111], v[172:175], v[116:119]
	v_mfma_f32_16x16x32_bf16 v[112:115], v[128:131], v[172:175], v[112:115]
	v_mfma_f32_16x16x32_bf16 v[92:95], v[108:111], v[180:183], v[92:95]
	v_mfma_f32_16x16x32_bf16 v[88:91], v[128:131], v[180:183], v[88:91]
	v_mfma_f32_16x16x32_bf16 v[76:79], v[108:111], v[210:213], v[76:79]
	v_mfma_f32_16x16x32_bf16 v[72:75], v[128:131], v[210:213], v[72:75]
	v_mfma_f32_16x16x32_bf16 v[132:135], v[144:147], v[160:163], 0
	v_mfma_f32_16x16x32_bf16 v[120:123], v[152:155], v[160:163], 0
	v_mfma_f32_16x16x32_bf16 v[100:103], v[144:147], v[168:171], 0
	v_mfma_f32_16x16x32_bf16 v[96:99], v[152:155], v[168:171], 0
	v_mfma_f32_16x16x32_bf16 v[84:87], v[144:147], v[176:179], 0
	v_mfma_f32_16x16x32_bf16 v[80:83], v[152:155], v[176:179], 0
	v_mfma_f32_16x16x32_bf16 v[68:71], v[144:147], v[206:209], 0
	v_mfma_f32_16x16x32_bf16 v[64:67], v[152:155], v[206:209], 0
	v_mfma_f32_16x16x32_bf16 v[132:135], v[148:151], v[164:167], v[132:135]
	v_mfma_f32_16x16x32_bf16 v[120:123], v[156:159], v[164:167], v[120:123]
	v_mfma_f32_16x16x32_bf16 v[100:103], v[148:151], v[172:175], v[100:103]
	v_mfma_f32_16x16x32_bf16 v[96:99], v[156:159], v[172:175], v[96:99]
	v_mfma_f32_16x16x32_bf16 v[84:87], v[148:151], v[180:183], v[84:87]
	v_mfma_f32_16x16x32_bf16 v[80:83], v[156:159], v[180:183], v[80:83]
	v_mfma_f32_16x16x32_bf16 v[68:71], v[148:151], v[210:213], v[68:71]
	v_mfma_f32_16x16x32_bf16 v[64:67], v[156:159], v[210:213], v[64:67]
	s_barrier
	s_setprio 0
	s_add_i32 s88, s69, s13
	s_add_u32 s98, s48, 0x80
	s_addc_u32 s99, s49, 0
	s_mov_b32 m0, s88
	ds_read_b128 v[160:163], v202 offset:16384
	ds_read_b128 v[164:167], v202 offset:17408
	ds_read_b128 v[168:171], v202 offset:18432
	ds_read_b128 v[172:175], v202 offset:19456
	ds_read_b128 v[176:179], v202 offset:20480
	ds_read_b128 v[180:183], v202 offset:21504
	ds_read_b128 v[206:209], v202 offset:22528
	ds_read_b128 v[210:213], v202 offset:23552
	global_load_lds_dwordx4 v184, s[48:49]
	s_add_i32 m0, s88, 0x2000
	s_add_u32 s88, s48, 0x40000
	s_addc_u32 s89, s49, 0
	s_add_i32 s90, s70, s13
	global_load_lds_dwordx4 v186, s[48:49]
	s_mov_b32 m0, s90
	s_add_u32 s100, s50, 0x80
	s_addc_u32 s101, s51, 0
	global_load_lds_dwordx4 v184, s[88:89]
	s_add_i32 m0, s90, 0x2000
	s_nop 0
	global_load_lds_dwordx4 v186, s[88:89]
	s_mov_b32 m0, s52
	s_nop 0
	global_load_lds_dwordx4 v184, s[50:51]
	s_mov_b32 m0, s53
	s_nop 0
	global_load_lds_dwordx4 v186, s[50:51]
	s_waitcnt vmcnt(8)
	s_waitcnt lgkmcnt(0)
	s_setprio 1
	s_barrier
	v_mfma_f32_16x16x32_bf16 v[60:63], v[104:107], v[160:163], 0
	v_mfma_f32_16x16x32_bf16 v[56:59], v[124:127], v[160:163], 0
	v_mfma_f32_16x16x32_bf16 v[44:47], v[104:107], v[168:171], 0
	v_mfma_f32_16x16x32_bf16 v[40:43], v[124:127], v[168:171], 0
	v_mfma_f32_16x16x32_bf16 v[28:31], v[104:107], v[176:179], 0
	v_mfma_f32_16x16x32_bf16 v[24:27], v[124:127], v[176:179], 0
	v_mfma_f32_16x16x32_bf16 v[12:15], v[104:107], v[206:209], 0
	v_mfma_f32_16x16x32_bf16 v[8:11], v[124:127], v[206:209], 0
	v_mfma_f32_16x16x32_bf16 v[60:63], v[108:111], v[164:167], v[60:63]
	v_mfma_f32_16x16x32_bf16 v[56:59], v[128:131], v[164:167], v[56:59]
	v_mfma_f32_16x16x32_bf16 v[44:47], v[108:111], v[172:175], v[44:47]
	v_mfma_f32_16x16x32_bf16 v[40:43], v[128:131], v[172:175], v[40:43]
	v_mfma_f32_16x16x32_bf16 v[28:31], v[108:111], v[180:183], v[28:31]
	v_mfma_f32_16x16x32_bf16 v[24:27], v[128:131], v[180:183], v[24:27]
	v_mfma_f32_16x16x32_bf16 v[12:15], v[108:111], v[210:213], v[12:15]
	v_mfma_f32_16x16x32_bf16 v[8:11], v[128:131], v[210:213], v[8:11]
	v_mfma_f32_16x16x32_bf16 v[52:55], v[144:147], v[160:163], 0
	v_mfma_f32_16x16x32_bf16 v[48:51], v[152:155], v[160:163], 0
	v_mfma_f32_16x16x32_bf16 v[36:39], v[144:147], v[168:171], 0
	v_mfma_f32_16x16x32_bf16 v[32:35], v[152:155], v[168:171], 0
	v_mfma_f32_16x16x32_bf16 v[20:23], v[144:147], v[176:179], 0
	v_mfma_f32_16x16x32_bf16 v[16:19], v[152:155], v[176:179], 0
	v_mfma_f32_16x16x32_bf16 v[4:7], v[144:147], v[206:209], 0
	v_mfma_f32_16x16x32_bf16 v[0:3], v[152:155], v[206:209], 0
	v_mfma_f32_16x16x32_bf16 v[52:55], v[148:151], v[164:167], v[52:55]
	v_mfma_f32_16x16x32_bf16 v[48:51], v[156:159], v[164:167], v[48:51]
	v_mfma_f32_16x16x32_bf16 v[36:39], v[148:151], v[172:175], v[36:39]
	v_mfma_f32_16x16x32_bf16 v[32:35], v[156:159], v[172:175], v[32:35]
	v_mfma_f32_16x16x32_bf16 v[20:23], v[148:151], v[180:183], v[20:23]
	v_mfma_f32_16x16x32_bf16 v[16:19], v[156:159], v[180:183], v[16:19]
	v_mfma_f32_16x16x32_bf16 v[4:7], v[148:151], v[210:213], v[4:7]
	v_mfma_f32_16x16x32_bf16 v[0:3], v[156:159], v[210:213], v[0:3]
	s_barrier
	s_setprio 0
	s_add_i32 s88, 0, 0x18000
	s_add_i32 s89, 0, 0x1c000
	v_add_u32_e32 v128, s88, v199
	v_add_u32_e32 v156, s89, v199
	ds_read_b128 v[104:107], v128
	ds_read_b128 v[108:111], v128 offset:1024
	ds_read_b128 v[124:127], v128 offset:2048
	ds_read_b128 v[128:131], v128 offset:3072
	ds_read_b128 v[144:147], v156
	ds_read_b128 v[148:151], v156 offset:1024
	ds_read_b128 v[152:155], v156 offset:2048
	ds_read_b128 v[156:159], v156 offset:3072
	s_add_u32 s50, s50, 0x40000
	s_addc_u32 s51, s51, 0
	s_mov_b32 m0, s54
	ds_read_b128 v[160:163], v202 offset:32768
	ds_read_b128 v[164:167], v202 offset:33792
	ds_read_b128 v[168:171], v202 offset:34816
	ds_read_b128 v[172:175], v202 offset:35840
	ds_read_b128 v[176:179], v202 offset:36864
	ds_read_b128 v[180:183], v202 offset:37888
	ds_read_b128 v[206:209], v202 offset:38912
	ds_read_b128 v[210:213], v202 offset:39936
	global_load_lds_dwordx4 v184, s[50:51]
	s_mov_b32 m0, s55
	s_nop 0
	global_load_lds_dwordx4 v186, s[50:51]
	s_waitcnt vmcnt(8)
	s_waitcnt lgkmcnt(0)
	s_setprio 1
	s_barrier
	v_mfma_f32_16x16x32_bf16 v[140:143], v[104:107], v[160:163], v[140:143]
	v_mfma_f32_16x16x32_bf16 v[136:139], v[124:127], v[160:163], v[136:139]
	v_mfma_f32_16x16x32_bf16 v[116:119], v[104:107], v[168:171], v[116:119]
	v_mfma_f32_16x16x32_bf16 v[112:115], v[124:127], v[168:171], v[112:115]
	v_mfma_f32_16x16x32_bf16 v[92:95], v[104:107], v[176:179], v[92:95]
	v_mfma_f32_16x16x32_bf16 v[88:91], v[124:127], v[176:179], v[88:91]
	v_mfma_f32_16x16x32_bf16 v[76:79], v[104:107], v[206:209], v[76:79]
	v_mfma_f32_16x16x32_bf16 v[72:75], v[124:127], v[206:209], v[72:75]
	v_mfma_f32_16x16x32_bf16 v[140:143], v[108:111], v[164:167], v[140:143]
	v_mfma_f32_16x16x32_bf16 v[136:139], v[128:131], v[164:167], v[136:139]
	v_mfma_f32_16x16x32_bf16 v[116:119], v[108:111], v[172:175], v[116:119]
	v_mfma_f32_16x16x32_bf16 v[112:115], v[128:131], v[172:175], v[112:115]
	v_mfma_f32_16x16x32_bf16 v[92:95], v[108:111], v[180:183], v[92:95]
	v_mfma_f32_16x16x32_bf16 v[88:91], v[128:131], v[180:183], v[88:91]
	v_mfma_f32_16x16x32_bf16 v[76:79], v[108:111], v[210:213], v[76:79]
	v_mfma_f32_16x16x32_bf16 v[72:75], v[128:131], v[210:213], v[72:75]
	v_mfma_f32_16x16x32_bf16 v[132:135], v[144:147], v[160:163], v[132:135]
	v_mfma_f32_16x16x32_bf16 v[120:123], v[152:155], v[160:163], v[120:123]
	v_mfma_f32_16x16x32_bf16 v[100:103], v[144:147], v[168:171], v[100:103]
	v_mfma_f32_16x16x32_bf16 v[96:99], v[152:155], v[168:171], v[96:99]
	v_mfma_f32_16x16x32_bf16 v[84:87], v[144:147], v[176:179], v[84:87]
	v_mfma_f32_16x16x32_bf16 v[80:83], v[152:155], v[176:179], v[80:83]
	v_mfma_f32_16x16x32_bf16 v[68:71], v[144:147], v[206:209], v[68:71]
	v_mfma_f32_16x16x32_bf16 v[64:67], v[152:155], v[206:209], v[64:67]
	v_mfma_f32_16x16x32_bf16 v[132:135], v[148:151], v[164:167], v[132:135]
	v_mfma_f32_16x16x32_bf16 v[120:123], v[156:159], v[164:167], v[120:123]
	v_mfma_f32_16x16x32_bf16 v[100:103], v[148:151], v[172:175], v[100:103]
	v_mfma_f32_16x16x32_bf16 v[96:99], v[156:159], v[172:175], v[96:99]
	v_mfma_f32_16x16x32_bf16 v[84:87], v[148:151], v[180:183], v[84:87]
	v_mfma_f32_16x16x32_bf16 v[80:83], v[156:159], v[180:183], v[80:83]
	v_mfma_f32_16x16x32_bf16 v[68:71], v[148:151], v[210:213], v[68:71]
	v_mfma_f32_16x16x32_bf16 v[64:67], v[156:159], v[210:213], v[64:67]
	s_barrier
	s_setprio 0
	s_add_i32 s50, s88, s13
	s_mov_b32 m0, s50
	ds_read_b128 v[160:163], v202 offset:49152
	ds_read_b128 v[164:167], v202 offset:50176
	ds_read_b128 v[168:171], v202 offset:51200
	ds_read_b128 v[172:175], v202 offset:52224
	ds_read_b128 v[176:179], v202 offset:53248
	ds_read_b128 v[180:183], v202 offset:54272
	ds_read_b128 v[206:209], v202 offset:55296
	ds_read_b128 v[210:213], v202 offset:56320
	global_load_lds_dwordx4 v184, s[98:99]
	s_add_i32 m0, s50, 0x2000
	s_add_u32 s48, s48, 0x40080
	s_addc_u32 s49, s49, 0
	s_add_i32 s50, s89, s13
	global_load_lds_dwordx4 v186, s[98:99]
	s_mov_b32 m0, s50
	s_nop 0
	global_load_lds_dwordx4 v184, s[48:49]
	s_add_i32 m0, s50, 0x2000
	s_nop 0
	global_load_lds_dwordx4 v186, s[48:49]
	s_mov_b32 m0, s61
	s_nop 0
	global_load_lds_dwordx4 v184, s[100:101]
	s_mov_b32 m0, s62
	s_nop 0
	global_load_lds_dwordx4 v186, s[100:101]
	s_waitcnt vmcnt(8)
	s_waitcnt lgkmcnt(0)
	s_setprio 1
	s_barrier
	v_mfma_f32_16x16x32_bf16 v[60:63], v[104:107], v[160:163], v[60:63]
	v_mfma_f32_16x16x32_bf16 v[56:59], v[124:127], v[160:163], v[56:59]
	v_mfma_f32_16x16x32_bf16 v[44:47], v[104:107], v[168:171], v[44:47]
	v_mfma_f32_16x16x32_bf16 v[40:43], v[124:127], v[168:171], v[40:43]
	v_mfma_f32_16x16x32_bf16 v[28:31], v[104:107], v[176:179], v[28:31]
	v_mfma_f32_16x16x32_bf16 v[24:27], v[124:127], v[176:179], v[24:27]
	v_mfma_f32_16x16x32_bf16 v[12:15], v[104:107], v[206:209], v[12:15]
	v_mfma_f32_16x16x32_bf16 v[8:11], v[124:127], v[206:209], v[8:11]
	v_mfma_f32_16x16x32_bf16 v[60:63], v[108:111], v[164:167], v[60:63]
	v_mfma_f32_16x16x32_bf16 v[56:59], v[128:131], v[164:167], v[56:59]
	v_mfma_f32_16x16x32_bf16 v[44:47], v[108:111], v[172:175], v[44:47]
	v_mfma_f32_16x16x32_bf16 v[40:43], v[128:131], v[172:175], v[40:43]
	v_mfma_f32_16x16x32_bf16 v[28:31], v[108:111], v[180:183], v[28:31]
	v_mfma_f32_16x16x32_bf16 v[24:27], v[128:131], v[180:183], v[24:27]
	v_mfma_f32_16x16x32_bf16 v[12:15], v[108:111], v[210:213], v[12:15]
	v_mfma_f32_16x16x32_bf16 v[8:11], v[128:131], v[210:213], v[8:11]
	v_mfma_f32_16x16x32_bf16 v[52:55], v[144:147], v[160:163], v[52:55]
	v_mfma_f32_16x16x32_bf16 v[48:51], v[152:155], v[160:163], v[48:51]
	v_mfma_f32_16x16x32_bf16 v[36:39], v[144:147], v[168:171], v[36:39]
	v_mfma_f32_16x16x32_bf16 v[32:35], v[152:155], v[168:171], v[32:35]
	v_mfma_f32_16x16x32_bf16 v[20:23], v[144:147], v[176:179], v[20:23]
	v_mfma_f32_16x16x32_bf16 v[16:19], v[152:155], v[176:179], v[16:19]
	v_mfma_f32_16x16x32_bf16 v[4:7], v[144:147], v[206:209], v[4:7]
	v_mfma_f32_16x16x32_bf16 v[0:3], v[152:155], v[206:209], v[0:3]
	v_mfma_f32_16x16x32_bf16 v[52:55], v[148:151], v[164:167], v[52:55]
	v_mfma_f32_16x16x32_bf16 v[48:51], v[156:159], v[164:167], v[48:51]
	v_mfma_f32_16x16x32_bf16 v[36:39], v[148:151], v[172:175], v[36:39]
	v_mfma_f32_16x16x32_bf16 v[32:35], v[156:159], v[172:175], v[32:35]
	v_mfma_f32_16x16x32_bf16 v[20:23], v[148:151], v[180:183], v[20:23]
	v_mfma_f32_16x16x32_bf16 v[16:19], v[156:159], v[180:183], v[16:19]
	v_mfma_f32_16x16x32_bf16 v[4:7], v[148:151], v[210:213], v[4:7]
	v_mfma_f32_16x16x32_bf16 v[0:3], v[156:159], v[210:213], v[0:3]
	s_barrier
	s_setprio 0
	s_add_i32 s87, s87, 2
	s_add_u32 s46, s46, 0x100
	s_addc_u32 s47, s47, 0
	s_add_u32 s85, s85, 0x100
	s_addc_u32 s86, s86, 0
	s_cmp_gt_u32 s87, 13
	s_cbranch_scc1 .Lkx_504

.Lkx_504:
	s_and_b64 vcc, exec, s[34:35]
	s_cbranch_vccz .LBB0_507
	s_barrier

.LBB0_551:
	s_ashr_i32 s57, s56, 31
	s_lshl_b64 s[22:23], s[56:57], 19
	s_add_u32 s58, s3, s22
	s_addc_u32 s59, s81, s23
	s_and_b64 s[22:23], s[6:7], exec
	s_cselect_b32 s9, s59, s63
	s_cselect_b32 s11, s58, s62
	s_ashr_i32 s55, s54, 31
	s_lshl_b64 s[22:23], s[54:55], 19
	s_add_u32 s60, s82, s22
	s_addc_u32 s61, s83, s23
	s_and_b64 s[22:23], s[6:7], exec
	s_cselect_b32 s13, s61, s65
	s_cselect_b32 s16, s60, s64
	s_add_u32 s62, s62, 0x40080
	s_addc_u32 s63, s63, 0
	s_add_u32 s22, s64, 0x100
	s_waitcnt lgkmcnt(0)
	s_addc_u32 s23, s65, 0
	s_mov_b32 s55, -2
	ds_read_b128 v[128:131], v173
	ds_read_b128 v[132:135], v173 offset:1024
	ds_read_b128 v[136:139], v173 offset:2048
	ds_read_b128 v[140:143], v173 offset:3072
	ds_read_b128 v[160:163], v179
	ds_read_b128 v[174:177], v179 offset:1024
	ds_read_b128 v[194:197], v179 offset:2048
	ds_read_b128 v[198:201], v179 offset:3072
	s_add_u32 s57, s62, 0xfffc0080
	s_addc_u32 s64, s63, -1
	s_cmp_eq_u32 s55, 12
	s_cselect_b32 s67, s9, s64
	s_cselect_b32 s66, s11, s57
	s_cselect_b32 s65, s13, s23
	s_cselect_b32 s64, s16, s22
	s_add_i32 m0, s86, 0xc000
	ds_read_b128 v[202:205], v183
	ds_read_b128 v[206:209], v183 offset:1024
	ds_read_b128 v[210:213], v183 offset:2048
	ds_read_b128 v[214:217], v183 offset:3072
	ds_read_b128 v[218:221], v183 offset:4096
	ds_read_b128 v[222:225], v183 offset:5120
	ds_read_b128 v[226:229], v183 offset:6144
	ds_read_b128 v[230:233], v183 offset:7168
	global_load_lds_dwordx4 v152, s[62:63]
	s_add_i32 m0, s86, 0xe000
	s_nop 0
	global_load_lds_dwordx4 v154, s[62:63]
	s_waitcnt vmcnt(8)
	s_waitcnt lgkmcnt(0)
	s_setprio 1
	s_barrier
	v_mfma_f32_16x16x32_bf16 v[124:127], v[128:131], v[202:205], 0
	v_mfma_f32_16x16x32_bf16 v[120:123], v[136:139], v[202:205], 0
	v_mfma_f32_16x16x32_bf16 v[108:111], v[128:131], v[210:213], 0
	v_mfma_f32_16x16x32_bf16 v[104:107], v[136:139], v[210:213], 0
	v_mfma_f32_16x16x32_bf16 v[92:95], v[128:131], v[218:221], 0
	v_mfma_f32_16x16x32_bf16 v[88:91], v[136:139], v[218:221], 0
	v_mfma_f32_16x16x32_bf16 v[76:79], v[128:131], v[226:229], 0
	v_mfma_f32_16x16x32_bf16 v[72:75], v[136:139], v[226:229], 0
	v_mfma_f32_16x16x32_bf16 v[124:127], v[132:135], v[206:209], v[124:127]
	v_mfma_f32_16x16x32_bf16 v[120:123], v[140:143], v[206:209], v[120:123]
	v_mfma_f32_16x16x32_bf16 v[108:111], v[132:135], v[214:217], v[108:111]
	v_mfma_f32_16x16x32_bf16 v[104:107], v[140:143], v[214:217], v[104:107]
	v_mfma_f32_16x16x32_bf16 v[92:95], v[132:135], v[222:225], v[92:95]
	v_mfma_f32_16x16x32_bf16 v[88:91], v[140:143], v[222:225], v[88:91]
	v_mfma_f32_16x16x32_bf16 v[76:79], v[132:135], v[230:233], v[76:79]
	v_mfma_f32_16x16x32_bf16 v[72:75], v[140:143], v[230:233], v[72:75]
	v_mfma_f32_16x16x32_bf16 v[116:119], v[160:163], v[202:205], 0
	v_mfma_f32_16x16x32_bf16 v[112:115], v[194:197], v[202:205], 0
	v_mfma_f32_16x16x32_bf16 v[100:103], v[160:163], v[210:213], 0
	v_mfma_f32_16x16x32_bf16 v[96:99], v[194:197], v[210:213], 0
	v_mfma_f32_16x16x32_bf16 v[84:87], v[160:163], v[218:221], 0
	v_mfma_f32_16x16x32_bf16 v[80:83], v[194:197], v[218:221], 0
	v_mfma_f32_16x16x32_bf16 v[68:71], v[160:163], v[226:229], 0
	v_mfma_f32_16x16x32_bf16 v[64:67], v[194:197], v[226:229], 0
	v_mfma_f32_16x16x32_bf16 v[116:119], v[174:177], v[206:209], v[116:119]
	v_mfma_f32_16x16x32_bf16 v[112:115], v[198:201], v[206:209], v[112:115]
	v_mfma_f32_16x16x32_bf16 v[100:103], v[174:177], v[214:217], v[100:103]
	v_mfma_f32_16x16x32_bf16 v[96:99], v[198:201], v[214:217], v[96:99]
	v_mfma_f32_16x16x32_bf16 v[84:87], v[174:177], v[222:225], v[84:87]
	v_mfma_f32_16x16x32_bf16 v[80:83], v[198:201], v[222:225], v[80:83]
	v_mfma_f32_16x16x32_bf16 v[68:71], v[174:177], v[230:233], v[68:71]
	v_mfma_f32_16x16x32_bf16 v[64:67], v[198:201], v[230:233], v[64:67]
	s_barrier
	s_setprio 0
	s_add_i32 s57, s0, s85
	s_add_u32 s98, s64, 0x80
	s_addc_u32 s99, s65, 0
	s_mov_b32 m0, s57
	ds_read_b128 v[202:205], v183 offset:16384
	ds_read_b128 v[206:209], v183 offset:17408
	ds_read_b128 v[210:213], v183 offset:18432
	ds_read_b128 v[214:217], v183 offset:19456
	ds_read_b128 v[218:221], v183 offset:20480
	ds_read_b128 v[222:225], v183 offset:21504
	ds_read_b128 v[226:229], v183 offset:22528
	ds_read_b128 v[230:233], v183 offset:23552
	global_load_lds_dwordx4 v144, s[64:65]
	s_add_i32 m0, s57, 0x2000
	s_add_u32 s68, s64, 0x40000
	s_addc_u32 s69, s65, 0
	s_add_i32 s57, s1, s85
	global_load_lds_dwordx4 v146, s[64:65]
	s_mov_b32 m0, s57
	s_add_u32 s100, s66, 0x80
	s_addc_u32 s101, s67, 0
	global_load_lds_dwordx4 v144, s[68:69]
	s_add_i32 m0, s57, 0x2000
	s_nop 0
	global_load_lds_dwordx4 v146, s[68:69]
	s_mov_b32 m0, s86
	s_nop 0
	global_load_lds_dwordx4 v144, s[66:67]
	s_mov_b32 m0, s87
	s_nop 0
	global_load_lds_dwordx4 v146, s[66:67]
	s_waitcnt vmcnt(8)
	s_waitcnt lgkmcnt(0)
	s_setprio 1
	s_barrier
	v_mfma_f32_16x16x32_bf16 v[60:63], v[128:131], v[202:205], 0
	v_mfma_f32_16x16x32_bf16 v[56:59], v[136:139], v[202:205], 0
	v_mfma_f32_16x16x32_bf16 v[44:47], v[128:131], v[210:213], 0
	v_mfma_f32_16x16x32_bf16 v[40:43], v[136:139], v[210:213], 0
	v_mfma_f32_16x16x32_bf16 v[28:31], v[128:131], v[218:221], 0
	v_mfma_f32_16x16x32_bf16 v[24:27], v[136:139], v[218:221], 0
	v_mfma_f32_16x16x32_bf16 v[12:15], v[128:131], v[226:229], 0
	v_mfma_f32_16x16x32_bf16 v[8:11], v[136:139], v[226:229], 0
	v_mfma_f32_16x16x32_bf16 v[60:63], v[132:135], v[206:209], v[60:63]
	v_mfma_f32_16x16x32_bf16 v[56:59], v[140:143], v[206:209], v[56:59]
	v_mfma_f32_16x16x32_bf16 v[44:47], v[132:135], v[214:217], v[44:47]
	v_mfma_f32_16x16x32_bf16 v[40:43], v[140:143], v[214:217], v[40:43]
	v_mfma_f32_16x16x32_bf16 v[28:31], v[132:135], v[222:225], v[28:31]
	v_mfma_f32_16x16x32_bf16 v[24:27], v[140:143], v[222:225], v[24:27]
	v_mfma_f32_16x16x32_bf16 v[12:15], v[132:135], v[230:233], v[12:15]
	v_mfma_f32_16x16x32_bf16 v[8:11], v[140:143], v[230:233], v[8:11]
	v_mfma_f32_16x16x32_bf16 v[52:55], v[160:163], v[202:205], 0
	v_mfma_f32_16x16x32_bf16 v[48:51], v[194:197], v[202:205], 0
	v_mfma_f32_16x16x32_bf16 v[36:39], v[160:163], v[210:213], 0
	v_mfma_f32_16x16x32_bf16 v[32:35], v[194:197], v[210:213], 0
	v_mfma_f32_16x16x32_bf16 v[20:23], v[160:163], v[218:221], 0
	v_mfma_f32_16x16x32_bf16 v[16:19], v[194:197], v[218:221], 0
	v_mfma_f32_16x16x32_bf16 v[4:7], v[160:163], v[226:229], 0
	v_mfma_f32_16x16x32_bf16 v[0:3], v[194:197], v[226:229], 0
	v_mfma_f32_16x16x32_bf16 v[52:55], v[174:177], v[206:209], v[52:55]
	v_mfma_f32_16x16x32_bf16 v[48:51], v[198:201], v[206:209], v[48:51]
	v_mfma_f32_16x16x32_bf16 v[36:39], v[174:177], v[214:217], v[36:39]
	v_mfma_f32_16x16x32_bf16 v[32:35], v[198:201], v[214:217], v[32:35]
	v_mfma_f32_16x16x32_bf16 v[20:23], v[174:177], v[222:225], v[20:23]
	v_mfma_f32_16x16x32_bf16 v[16:19], v[198:201], v[222:225], v[16:19]
	v_mfma_f32_16x16x32_bf16 v[4:7], v[174:177], v[230:233], v[4:7]
	v_mfma_f32_16x16x32_bf16 v[0:3], v[198:201], v[230:233], v[0:3]
	s_barrier
	s_setprio 0
	s_add_i32 s57, 0, 0x18000
	s_add_i32 s68, 0, 0x1c000
	v_add_u32_e32 v140, s57, v169
	v_add_u32_e32 v148, s68, v169
	ds_read_b128 v[128:131], v140
	ds_read_b128 v[132:135], v140 offset:1024
	ds_read_b128 v[136:139], v140 offset:2048
	ds_read_b128 v[140:143], v140 offset:3072
	ds_read_b128 v[160:163], v148
	ds_read_b128 v[174:177], v148 offset:1024
	ds_read_b128 v[194:197], v148 offset:2048
	ds_read_b128 v[198:201], v148 offset:3072
	s_add_u32 s66, s66, 0x40000
	s_addc_u32 s67, s67, 0
	s_mov_b32 m0, s88
	ds_read_b128 v[202:205], v183 offset:32768
	ds_read_b128 v[206:209], v183 offset:33792
	ds_read_b128 v[210:213], v183 offset:34816
	ds_read_b128 v[214:217], v183 offset:35840
	ds_read_b128 v[218:221], v183 offset:36864
	ds_read_b128 v[222:225], v183 offset:37888
	ds_read_b128 v[226:229], v183 offset:38912
	ds_read_b128 v[230:233], v183 offset:39936
	global_load_lds_dwordx4 v144, s[66:67]
	s_mov_b32 m0, s89
	s_nop 0
	global_load_lds_dwordx4 v146, s[66:67]
	s_waitcnt vmcnt(8)
	s_waitcnt lgkmcnt(0)
	s_setprio 1
	s_barrier
	v_mfma_f32_16x16x32_bf16 v[124:127], v[128:131], v[202:205], v[124:127]
	v_mfma_f32_16x16x32_bf16 v[120:123], v[136:139], v[202:205], v[120:123]
	v_mfma_f32_16x16x32_bf16 v[108:111], v[128:131], v[210:213], v[108:111]
	v_mfma_f32_16x16x32_bf16 v[104:107], v[136:139], v[210:213], v[104:107]
	v_mfma_f32_16x16x32_bf16 v[92:95], v[128:131], v[218:221], v[92:95]
	v_mfma_f32_16x16x32_bf16 v[88:91], v[136:139], v[218:221], v[88:91]
	v_mfma_f32_16x16x32_bf16 v[76:79], v[128:131], v[226:229], v[76:79]
	v_mfma_f32_16x16x32_bf16 v[72:75], v[136:139], v[226:229], v[72:75]
	v_mfma_f32_16x16x32_bf16 v[124:127], v[132:135], v[206:209], v[124:127]
	v_mfma_f32_16x16x32_bf16 v[120:123], v[140:143], v[206:209], v[120:123]
	v_mfma_f32_16x16x32_bf16 v[108:111], v[132:135], v[214:217], v[108:111]
	v_mfma_f32_16x16x32_bf16 v[104:107], v[140:143], v[214:217], v[104:107]
	v_mfma_f32_16x16x32_bf16 v[92:95], v[132:135], v[222:225], v[92:95]
	v_mfma_f32_16x16x32_bf16 v[88:91], v[140:143], v[222:225], v[88:91]
	v_mfma_f32_16x16x32_bf16 v[76:79], v[132:135], v[230:233], v[76:79]
	v_mfma_f32_16x16x32_bf16 v[72:75], v[140:143], v[230:233], v[72:75]
	v_mfma_f32_16x16x32_bf16 v[116:119], v[160:163], v[202:205], v[116:119]
	v_mfma_f32_16x16x32_bf16 v[112:115], v[194:197], v[202:205], v[112:115]
	v_mfma_f32_16x16x32_bf16 v[100:103], v[160:163], v[210:213], v[100:103]
	v_mfma_f32_16x16x32_bf16 v[96:99], v[194:197], v[210:213], v[96:99]
	v_mfma_f32_16x16x32_bf16 v[84:87], v[160:163], v[218:221], v[84:87]
	v_mfma_f32_16x16x32_bf16 v[80:83], v[194:197], v[218:221], v[80:83]
	v_mfma_f32_16x16x32_bf16 v[68:71], v[160:163], v[226:229], v[68:71]
	v_mfma_f32_16x16x32_bf16 v[64:67], v[194:197], v[226:229], v[64:67]
	v_mfma_f32_16x16x32_bf16 v[116:119], v[174:177], v[206:209], v[116:119]
	v_mfma_f32_16x16x32_bf16 v[112:115], v[198:201], v[206:209], v[112:115]
	v_mfma_f32_16x16x32_bf16 v[100:103], v[174:177], v[214:217], v[100:103]
	v_mfma_f32_16x16x32_bf16 v[96:99], v[198:201], v[214:217], v[96:99]
	v_mfma_f32_16x16x32_bf16 v[84:87], v[174:177], v[222:225], v[84:87]
	v_mfma_f32_16x16x32_bf16 v[80:83], v[198:201], v[222:225], v[80:83]
	v_mfma_f32_16x16x32_bf16 v[68:71], v[174:177], v[230:233], v[68:71]
	v_mfma_f32_16x16x32_bf16 v[64:67], v[198:201], v[230:233], v[64:67]
	s_barrier
	s_setprio 0
	s_add_i32 s57, s57, s85
	s_mov_b32 m0, s57
	ds_read_b128 v[202:205], v183 offset:49152
	ds_read_b128 v[206:209], v183 offset:50176
	ds_read_b128 v[210:213], v183 offset:51200
	ds_read_b128 v[214:217], v183 offset:52224
	ds_read_b128 v[218:221], v183 offset:53248
	ds_read_b128 v[222:225], v183 offset:54272
	ds_read_b128 v[226:229], v183 offset:55296
	ds_read_b128 v[230:233], v183 offset:56320
	global_load_lds_dwordx4 v144, s[98:99]
	s_add_i32 m0, s57, 0x2000
	s_add_u32 s64, s64, 0x40080
	s_addc_u32 s65, s65, 0
	s_add_i32 s57, s68, s85
	global_load_lds_dwordx4 v146, s[98:99]
	s_mov_b32 m0, s57
	s_nop 0
	global_load_lds_dwordx4 v144, s[64:65]
	s_add_i32 m0, s57, 0x2000
	s_nop 0
	global_load_lds_dwordx4 v146, s[64:65]
	s_mov_b32 m0, s94
	s_nop 0
	global_load_lds_dwordx4 v144, s[100:101]
	s_mov_b32 m0, s95
	s_nop 0
	global_load_lds_dwordx4 v146, s[100:101]
	s_waitcnt vmcnt(8)
	s_waitcnt lgkmcnt(0)
	s_setprio 1
	s_barrier
	v_mfma_f32_16x16x32_bf16 v[60:63], v[128:131], v[202:205], v[60:63]
	v_mfma_f32_16x16x32_bf16 v[56:59], v[136:139], v[202:205], v[56:59]
	v_mfma_f32_16x16x32_bf16 v[44:47], v[128:131], v[210:213], v[44:47]
	v_mfma_f32_16x16x32_bf16 v[40:43], v[136:139], v[210:213], v[40:43]
	v_mfma_f32_16x16x32_bf16 v[28:31], v[128:131], v[218:221], v[28:31]
	v_mfma_f32_16x16x32_bf16 v[24:27], v[136:139], v[218:221], v[24:27]
	v_mfma_f32_16x16x32_bf16 v[12:15], v[128:131], v[226:229], v[12:15]
	v_mfma_f32_16x16x32_bf16 v[8:11], v[136:139], v[226:229], v[8:11]
	v_mfma_f32_16x16x32_bf16 v[60:63], v[132:135], v[206:209], v[60:63]
	v_mfma_f32_16x16x32_bf16 v[56:59], v[140:143], v[206:209], v[56:59]
	v_mfma_f32_16x16x32_bf16 v[44:47], v[132:135], v[214:217], v[44:47]
	v_mfma_f32_16x16x32_bf16 v[40:43], v[140:143], v[214:217], v[40:43]
	v_mfma_f32_16x16x32_bf16 v[28:31], v[132:135], v[222:225], v[28:31]
	v_mfma_f32_16x16x32_bf16 v[24:27], v[140:143], v[222:225], v[24:27]
	v_mfma_f32_16x16x32_bf16 v[12:15], v[132:135], v[230:233], v[12:15]
	v_mfma_f32_16x16x32_bf16 v[8:11], v[140:143], v[230:233], v[8:11]
	v_mfma_f32_16x16x32_bf16 v[52:55], v[160:163], v[202:205], v[52:55]
	v_mfma_f32_16x16x32_bf16 v[48:51], v[194:197], v[202:205], v[48:51]
	v_mfma_f32_16x16x32_bf16 v[36:39], v[160:163], v[210:213], v[36:39]
	v_mfma_f32_16x16x32_bf16 v[32:35], v[194:197], v[210:213], v[32:35]
	v_mfma_f32_16x16x32_bf16 v[20:23], v[160:163], v[218:221], v[20:23]
	v_mfma_f32_16x16x32_bf16 v[16:19], v[194:197], v[218:221], v[16:19]
	v_mfma_f32_16x16x32_bf16 v[4:7], v[160:163], v[226:229], v[4:7]
	v_mfma_f32_16x16x32_bf16 v[0:3], v[194:197], v[226:229], v[0:3]
	v_mfma_f32_16x16x32_bf16 v[52:55], v[174:177], v[206:209], v[52:55]
	v_mfma_f32_16x16x32_bf16 v[48:51], v[198:201], v[206:209], v[48:51]
	v_mfma_f32_16x16x32_bf16 v[36:39], v[174:177], v[214:217], v[36:39]
	v_mfma_f32_16x16x32_bf16 v[32:35], v[198:201], v[214:217], v[32:35]
	v_mfma_f32_16x16x32_bf16 v[20:23], v[174:177], v[222:225], v[20:23]
	v_mfma_f32_16x16x32_bf16 v[16:19], v[198:201], v[222:225], v[16:19]
	v_mfma_f32_16x16x32_bf16 v[4:7], v[174:177], v[230:233], v[4:7]
	v_mfma_f32_16x16x32_bf16 v[0:3], v[198:201], v[230:233], v[0:3]
	s_barrier
	s_setprio 0
	s_add_i32 s55, s55, 2
	s_add_u32 s62, s62, 0x100
	s_addc_u32 s63, s63, 0
	s_add_u32 s22, s22, 0x100
	s_addc_u32 s23, s23, 0
	s_cmp_gt_u32 s55, 13
	s_cbranch_scc1 .Lkx_552

.Lkx_552:
	s_and_b64 vcc, exec, s[44:45]
	s_cbranch_vccz .LBB0_555
	s_barrier

.LBB0_743:
	s_ashr_i32 s35, s34, 31
	s_lshl_b64 s[36:37], s[34:35], 17
	s_add_u32 s36, s13, s36
	s_addc_u32 s37, s22, s37
	s_and_b64 s[38:39], s[4:5], exec
	s_cselect_b32 s35, s37, s43
	s_cselect_b32 s82, s36, s42
	s_ashr_i32 s31, s30, 31
	s_lshl_b64 s[38:39], s[30:31], 17
	s_add_u32 s38, s23, s38
	s_addc_u32 s39, s58, s39
	s_and_b64 s[44:45], s[4:5], exec
	s_cselect_b32 s31, s39, s41
	s_cselect_b32 s83, s38, s40
	s_mov_b64 s[48:49], 0
	s_mov_b64 s[44:45], -1
	s_mov_b64 s[46:47], 0
	s_add_u32 s54, s42, s48
	s_addc_u32 s55, s43, s49
	s_add_u32 s52, s54, 0x100
	s_addc_u32 s53, s55, 0
	s_and_b64 s[50:51], s[46:47], exec
	s_cselect_b32 s51, s35, s53
	s_cselect_b32 s50, s82, s52
	s_add_u32 s48, s40, s48
	s_addc_u32 s49, s41, s49
	s_add_u32 s48, s48, 0x100
	s_addc_u32 s49, s49, 0
	s_and_b64 s[46:47], s[46:47], exec
	s_cselect_b32 s53, s31, s49
	s_cselect_b32 s52, s83, s48
	s_cselect_b32 s98, 1, 0
	s_add_u32 s56, s54, 0x10080
	ds_read_b128 v[150:153], v144
	ds_read_b128 v[154:157], v144 offset:1024
	ds_read_b128 v[158:161], v144 offset:2048
	ds_read_b128 v[162:165], v144 offset:3072
	ds_read_b128 v[166:169], v145
	ds_read_b128 v[170:173], v145 offset:1024
	ds_read_b128 v[174:177], v145 offset:2048
	ds_read_b128 v[178:181], v145 offset:3072
	s_addc_u32 s57, s55, 0
	s_add_i32 s93, s74, s60
	s_add_i32 m0, s61, 0xc000
	s_add_i32 s94, s61, 0xe000
	s_add_i32 s90, s93, 0x2000
	s_add_u32 s54, s52, 0x10000
	s_addc_u32 s55, s53, 0
	s_add_i32 s92, s75, s60
	s_add_i32 s91, s92, 0x2000
	s_add_i32 s89, 0, 0x18000
	s_add_i32 s88, 0, 0x1c000
	s_add_u32 s48, s50, 0x10000
	s_addc_u32 s49, s51, 0
	s_add_i32 s87, s89, s60
	s_add_i32 s85, s87, 0x2000
	s_add_u32 s46, s52, 0x10080
	s_addc_u32 s47, s53, 0
	s_add_i32 s86, s88, s60
	s_add_i32 s84, s86, 0x2000
	v_lshl_add_u64 v[138:139], s[56:57], 0, v[130:131]
	ds_read_b128 v[182:185], v146
	ds_read_b128 v[186:189], v146 offset:1024
	ds_read_b128 v[190:193], v146 offset:2048
	ds_read_b128 v[194:197], v146 offset:3072
	ds_read_b128 v[198:201], v146 offset:4096
	ds_read_b128 v[202:205], v146 offset:5120
	ds_read_b128 v[206:209], v146 offset:6144
	ds_read_b128 v[210:213], v146 offset:7168
	global_load_lds_dwordx4 v[138:139], off
	v_lshl_add_u64 v[138:139], s[56:57], 0, v[128:129]
	s_mov_b32 m0, s94
	s_nop 0
	global_load_lds_dwordx4 v[138:139], off
	s_waitcnt vmcnt(8)
	s_waitcnt lgkmcnt(0)
	s_setprio 1
	s_cmp_lg_u32 s98, 0
	s_cbranch_scc0 .Lkv_nopf_pk
	v_lshl_add_u32 v138, s18, 8, v141
	v_ashrrev_i32_e32 v139, 31, v138
	v_lshl_add_u64 v[138:139], v[138:139], 4, s[14:15]
	global_load_dwordx4 v[222:225], v[138:139], off
	global_load_dwordx4 v[226:229], v[138:139], off offset:256
	global_load_dwordx4 v[230:233], v[138:139], off offset:512
	global_load_dwordx4 v[234:237], v[138:139], off offset:768
	global_load_dwordx4 v[238:241], v[138:139], off offset:2048
	global_load_dwordx4 v[242:245], v[138:139], off offset:2304
	global_load_dwordx4 v[248:251], v[138:139], off offset:2560
	global_load_dwordx4 v[252:255], v[138:139], off offset:2816
.Lkv_nopf_pk:
	s_barrier
	v_mfma_f32_16x16x32_bf16 v[124:127], v[150:153], v[182:185], 0
	v_mfma_f32_16x16x32_bf16 v[120:123], v[158:161], v[182:185], 0
	v_mfma_f32_16x16x32_bf16 v[108:111], v[150:153], v[190:193], 0
	v_mfma_f32_16x16x32_bf16 v[104:107], v[158:161], v[190:193], 0
	v_mfma_f32_16x16x32_bf16 v[92:95], v[150:153], v[198:201], 0
	v_mfma_f32_16x16x32_bf16 v[88:91], v[158:161], v[198:201], 0
	v_mfma_f32_16x16x32_bf16 v[76:79], v[150:153], v[206:209], 0
	v_mfma_f32_16x16x32_bf16 v[72:75], v[158:161], v[206:209], 0
	v_mfma_f32_16x16x32_bf16 v[124:127], v[154:157], v[186:189], v[124:127]
	v_mfma_f32_16x16x32_bf16 v[120:123], v[162:165], v[186:189], v[120:123]
	v_mfma_f32_16x16x32_bf16 v[108:111], v[154:157], v[194:197], v[108:111]
	v_mfma_f32_16x16x32_bf16 v[104:107], v[162:165], v[194:197], v[104:107]
	v_mfma_f32_16x16x32_bf16 v[92:95], v[154:157], v[202:205], v[92:95]
	v_mfma_f32_16x16x32_bf16 v[88:91], v[162:165], v[202:205], v[88:91]
	v_mfma_f32_16x16x32_bf16 v[76:79], v[154:157], v[210:213], v[76:79]
	v_mfma_f32_16x16x32_bf16 v[72:75], v[162:165], v[210:213], v[72:75]
	v_mfma_f32_16x16x32_bf16 v[116:119], v[166:169], v[182:185], 0
	v_mfma_f32_16x16x32_bf16 v[112:115], v[174:177], v[182:185], 0
	v_mfma_f32_16x16x32_bf16 v[100:103], v[166:169], v[190:193], 0
	v_mfma_f32_16x16x32_bf16 v[96:99], v[174:177], v[190:193], 0
	v_mfma_f32_16x16x32_bf16 v[84:87], v[166:169], v[198:201], 0
	v_mfma_f32_16x16x32_bf16 v[80:83], v[174:177], v[198:201], 0
	v_mfma_f32_16x16x32_bf16 v[68:71], v[166:169], v[206:209], 0
	v_mfma_f32_16x16x32_bf16 v[64:67], v[174:177], v[206:209], 0
	v_mfma_f32_16x16x32_bf16 v[116:119], v[170:173], v[186:189], v[116:119]
	v_mfma_f32_16x16x32_bf16 v[112:115], v[178:181], v[186:189], v[112:115]
	v_mfma_f32_16x16x32_bf16 v[100:103], v[170:173], v[194:197], v[100:103]
	v_mfma_f32_16x16x32_bf16 v[96:99], v[178:181], v[194:197], v[96:99]
	v_mfma_f32_16x16x32_bf16 v[84:87], v[170:173], v[202:205], v[84:87]
	v_mfma_f32_16x16x32_bf16 v[80:83], v[178:181], v[202:205], v[80:83]
	v_mfma_f32_16x16x32_bf16 v[68:71], v[170:173], v[210:213], v[68:71]
	v_mfma_f32_16x16x32_bf16 v[64:67], v[178:181], v[210:213], v[64:67]
	s_barrier
	s_setprio 0
	s_mov_b32 m0, s93
	v_lshl_add_u64 v[138:139], s[52:53], 0, v[130:131]
	ds_read_b128 v[182:185], v146 offset:16384
	ds_read_b128 v[186:189], v146 offset:17408
	ds_read_b128 v[190:193], v146 offset:18432
	ds_read_b128 v[194:197], v146 offset:19456
	ds_read_b128 v[198:201], v146 offset:20480
	ds_read_b128 v[202:205], v146 offset:21504
	ds_read_b128 v[206:209], v146 offset:22528
	ds_read_b128 v[210:213], v146 offset:23552
	global_load_lds_dwordx4 v[138:139], off
	v_lshl_add_u64 v[214:215], s[52:53], 0, v[128:129]
	s_mov_b32 m0, s90
	v_lshl_add_u64 v[216:217], s[54:55], 0, v[130:131]
	global_load_lds_dwordx4 v[214:215], off
	s_mov_b32 m0, s92
	v_lshl_add_u64 v[218:219], s[50:51], 0, v[128:129]
	global_load_lds_dwordx4 v[216:217], off
	v_lshl_add_u64 v[216:217], s[54:55], 0, v[128:129]
	s_mov_b32 m0, s91
	s_nop 0
	global_load_lds_dwordx4 v[216:217], off
	v_lshl_add_u64 v[216:217], s[50:51], 0, v[130:131]
	s_mov_b32 m0, s61
	s_nop 0
	global_load_lds_dwordx4 v[216:217], off
	s_mov_b32 m0, s62
	s_nop 0
	global_load_lds_dwordx4 v[218:219], off
	s_waitcnt vmcnt(8)
	s_waitcnt lgkmcnt(0)
	s_setprio 1
	s_barrier
	v_mfma_f32_16x16x32_bf16 v[60:63], v[150:153], v[182:185], 0
	v_mfma_f32_16x16x32_bf16 v[56:59], v[158:161], v[182:185], 0
	v_mfma_f32_16x16x32_bf16 v[44:47], v[150:153], v[190:193], 0
	v_mfma_f32_16x16x32_bf16 v[40:43], v[158:161], v[190:193], 0
	v_mfma_f32_16x16x32_bf16 v[28:31], v[150:153], v[198:201], 0
	v_mfma_f32_16x16x32_bf16 v[24:27], v[158:161], v[198:201], 0
	v_mfma_f32_16x16x32_bf16 v[12:15], v[150:153], v[206:209], 0
	v_mfma_f32_16x16x32_bf16 v[8:11], v[158:161], v[206:209], 0
	v_mfma_f32_16x16x32_bf16 v[60:63], v[154:157], v[186:189], v[60:63]
	v_mfma_f32_16x16x32_bf16 v[56:59], v[162:165], v[186:189], v[56:59]
	v_mfma_f32_16x16x32_bf16 v[44:47], v[154:157], v[194:197], v[44:47]
	v_mfma_f32_16x16x32_bf16 v[40:43], v[162:165], v[194:197], v[40:43]
	v_mfma_f32_16x16x32_bf16 v[28:31], v[154:157], v[202:205], v[28:31]
	v_mfma_f32_16x16x32_bf16 v[24:27], v[162:165], v[202:205], v[24:27]
	v_mfma_f32_16x16x32_bf16 v[12:15], v[154:157], v[210:213], v[12:15]
	v_mfma_f32_16x16x32_bf16 v[8:11], v[162:165], v[210:213], v[8:11]
	v_mfma_f32_16x16x32_bf16 v[52:55], v[166:169], v[182:185], 0
	v_mfma_f32_16x16x32_bf16 v[48:51], v[174:177], v[182:185], 0
	v_mfma_f32_16x16x32_bf16 v[36:39], v[166:169], v[190:193], 0
	v_mfma_f32_16x16x32_bf16 v[32:35], v[174:177], v[190:193], 0
	v_mfma_f32_16x16x32_bf16 v[20:23], v[166:169], v[198:201], 0
	v_mfma_f32_16x16x32_bf16 v[16:19], v[174:177], v[198:201], 0
	v_mfma_f32_16x16x32_bf16 v[4:7], v[166:169], v[206:209], 0
	v_mfma_f32_16x16x32_bf16 v[0:3], v[174:177], v[206:209], 0
	v_mfma_f32_16x16x32_bf16 v[52:55], v[170:173], v[186:189], v[52:55]
	v_mfma_f32_16x16x32_bf16 v[48:51], v[178:181], v[186:189], v[48:51]
	v_mfma_f32_16x16x32_bf16 v[36:39], v[170:173], v[194:197], v[36:39]
	v_mfma_f32_16x16x32_bf16 v[32:35], v[178:181], v[194:197], v[32:35]
	v_mfma_f32_16x16x32_bf16 v[20:23], v[170:173], v[202:205], v[20:23]
	v_mfma_f32_16x16x32_bf16 v[16:19], v[178:181], v[202:205], v[16:19]
	v_mfma_f32_16x16x32_bf16 v[4:7], v[170:173], v[210:213], v[4:7]
	v_mfma_f32_16x16x32_bf16 v[0:3], v[178:181], v[210:213], v[0:3]
	s_barrier
	s_setprio 0
	v_add_u32_e32 v132, s89, v143
	ds_read_b128 v[150:153], v132
	ds_read_b128 v[154:157], v132 offset:1024
	ds_read_b128 v[158:161], v132 offset:2048
	ds_read_b128 v[162:165], v132 offset:3072
	v_add_u32_e32 v132, s88, v143
	ds_read_b128 v[166:169], v132
	ds_read_b128 v[170:173], v132 offset:1024
	ds_read_b128 v[174:177], v132 offset:2048
	ds_read_b128 v[178:181], v132 offset:3072
	s_mov_b32 m0, s63
	v_lshl_add_u64 v[220:221], s[48:49], 0, v[130:131]
	ds_read_b128 v[182:185], v146 offset:32768
	ds_read_b128 v[186:189], v146 offset:33792
	ds_read_b128 v[190:193], v146 offset:34816
	ds_read_b128 v[194:197], v146 offset:35840
	ds_read_b128 v[198:201], v146 offset:36864
	ds_read_b128 v[202:205], v146 offset:37888
	ds_read_b128 v[206:209], v146 offset:38912
	ds_read_b128 v[210:213], v146 offset:39936
	global_load_lds_dwordx4 v[220:221], off
	v_lshl_add_u64 v[220:221], s[48:49], 0, v[128:129]
	s_mov_b32 m0, s64
	s_nop 0
	global_load_lds_dwordx4 v[220:221], off
	s_waitcnt vmcnt(8)
	s_waitcnt lgkmcnt(0)
	s_setprio 1
	s_barrier
	v_mfma_f32_16x16x32_bf16 v[124:127], v[150:153], v[182:185], v[124:127]
	v_mfma_f32_16x16x32_bf16 v[120:123], v[158:161], v[182:185], v[120:123]
	v_mfma_f32_16x16x32_bf16 v[108:111], v[150:153], v[190:193], v[108:111]
	v_mfma_f32_16x16x32_bf16 v[104:107], v[158:161], v[190:193], v[104:107]
	v_mfma_f32_16x16x32_bf16 v[92:95], v[150:153], v[198:201], v[92:95]
	v_mfma_f32_16x16x32_bf16 v[88:91], v[158:161], v[198:201], v[88:91]
	v_mfma_f32_16x16x32_bf16 v[76:79], v[150:153], v[206:209], v[76:79]
	v_mfma_f32_16x16x32_bf16 v[72:75], v[158:161], v[206:209], v[72:75]
	v_mfma_f32_16x16x32_bf16 v[124:127], v[154:157], v[186:189], v[124:127]
	v_mfma_f32_16x16x32_bf16 v[120:123], v[162:165], v[186:189], v[120:123]
	v_mfma_f32_16x16x32_bf16 v[108:111], v[154:157], v[194:197], v[108:111]
	v_mfma_f32_16x16x32_bf16 v[104:107], v[162:165], v[194:197], v[104:107]
	v_mfma_f32_16x16x32_bf16 v[92:95], v[154:157], v[202:205], v[92:95]
	v_mfma_f32_16x16x32_bf16 v[88:91], v[162:165], v[202:205], v[88:91]
	v_mfma_f32_16x16x32_bf16 v[76:79], v[154:157], v[210:213], v[76:79]
	v_mfma_f32_16x16x32_bf16 v[72:75], v[162:165], v[210:213], v[72:75]
	v_mfma_f32_16x16x32_bf16 v[116:119], v[166:169], v[182:185], v[116:119]
	v_mfma_f32_16x16x32_bf16 v[112:115], v[174:177], v[182:185], v[112:115]
	v_mfma_f32_16x16x32_bf16 v[100:103], v[166:169], v[190:193], v[100:103]
	v_mfma_f32_16x16x32_bf16 v[96:99], v[174:177], v[190:193], v[96:99]
	v_mfma_f32_16x16x32_bf16 v[84:87], v[166:169], v[198:201], v[84:87]
	v_mfma_f32_16x16x32_bf16 v[80:83], v[174:177], v[198:201], v[80:83]
	v_mfma_f32_16x16x32_bf16 v[68:71], v[166:169], v[206:209], v[68:71]
	v_mfma_f32_16x16x32_bf16 v[64:67], v[174:177], v[206:209], v[64:67]
	v_mfma_f32_16x16x32_bf16 v[116:119], v[170:173], v[186:189], v[116:119]
	v_mfma_f32_16x16x32_bf16 v[112:115], v[178:181], v[186:189], v[112:115]
	v_mfma_f32_16x16x32_bf16 v[100:103], v[170:173], v[194:197], v[100:103]
	v_mfma_f32_16x16x32_bf16 v[96:99], v[178:181], v[194:197], v[96:99]
	v_mfma_f32_16x16x32_bf16 v[84:87], v[170:173], v[202:205], v[84:87]
	v_mfma_f32_16x16x32_bf16 v[80:83], v[178:181], v[202:205], v[80:83]
	v_mfma_f32_16x16x32_bf16 v[68:71], v[170:173], v[210:213], v[68:71]
	v_mfma_f32_16x16x32_bf16 v[64:67], v[178:181], v[210:213], v[64:67]
	s_barrier
	s_setprio 0
	s_mov_b32 m0, s87
	v_lshl_add_u64 v[138:139], v[138:139], 0, s[16:17]
	ds_read_b128 v[182:185], v146 offset:49152
	ds_read_b128 v[186:189], v146 offset:50176
	ds_read_b128 v[190:193], v146 offset:51200
	ds_read_b128 v[194:197], v146 offset:52224
	ds_read_b128 v[198:201], v146 offset:53248
	ds_read_b128 v[202:205], v146 offset:54272
	ds_read_b128 v[206:209], v146 offset:55296
	ds_read_b128 v[210:213], v146 offset:56320
	global_load_lds_dwordx4 v[138:139], off
	v_lshl_add_u64 v[138:139], v[214:215], 0, s[16:17]
	s_mov_b32 m0, s85
	s_nop 0
	global_load_lds_dwordx4 v[138:139], off
	v_lshl_add_u64 v[138:139], s[46:47], 0, v[130:131]
	s_mov_b32 m0, s86
	s_nop 0
	global_load_lds_dwordx4 v[138:139], off
	v_lshl_add_u64 v[138:139], s[46:47], 0, v[128:129]
	s_mov_b32 m0, s84
	s_nop 0
	global_load_lds_dwordx4 v[138:139], off
	v_lshl_add_u64 v[138:139], v[216:217], 0, s[16:17]
	s_mov_b32 m0, s70
	s_nop 0
	global_load_lds_dwordx4 v[138:139], off
	v_lshl_add_u64 v[138:139], v[218:219], 0, s[16:17]
	s_mov_b32 m0, s71
	s_nop 0
	global_load_lds_dwordx4 v[138:139], off
	s_waitcnt vmcnt(8)
	s_waitcnt lgkmcnt(0)
	s_setprio 1
	s_barrier
	v_mfma_f32_16x16x32_bf16 v[60:63], v[150:153], v[182:185], v[60:63]
	v_mfma_f32_16x16x32_bf16 v[56:59], v[158:161], v[182:185], v[56:59]
	v_mfma_f32_16x16x32_bf16 v[44:47], v[150:153], v[190:193], v[44:47]
	v_mfma_f32_16x16x32_bf16 v[40:43], v[158:161], v[190:193], v[40:43]
	v_mfma_f32_16x16x32_bf16 v[28:31], v[150:153], v[198:201], v[28:31]
	v_mfma_f32_16x16x32_bf16 v[24:27], v[158:161], v[198:201], v[24:27]
	v_mfma_f32_16x16x32_bf16 v[12:15], v[150:153], v[206:209], v[12:15]
	v_mfma_f32_16x16x32_bf16 v[8:11], v[158:161], v[206:209], v[8:11]
	v_mfma_f32_16x16x32_bf16 v[60:63], v[154:157], v[186:189], v[60:63]
	v_mfma_f32_16x16x32_bf16 v[56:59], v[162:165], v[186:189], v[56:59]
	v_mfma_f32_16x16x32_bf16 v[44:47], v[154:157], v[194:197], v[44:47]
	v_mfma_f32_16x16x32_bf16 v[40:43], v[162:165], v[194:197], v[40:43]
	v_mfma_f32_16x16x32_bf16 v[28:31], v[154:157], v[202:205], v[28:31]
	v_mfma_f32_16x16x32_bf16 v[24:27], v[162:165], v[202:205], v[24:27]
	v_mfma_f32_16x16x32_bf16 v[12:15], v[154:157], v[210:213], v[12:15]
	v_mfma_f32_16x16x32_bf16 v[8:11], v[162:165], v[210:213], v[8:11]
	v_mfma_f32_16x16x32_bf16 v[52:55], v[166:169], v[182:185], v[52:55]
	v_mfma_f32_16x16x32_bf16 v[48:51], v[174:177], v[182:185], v[48:51]
	v_mfma_f32_16x16x32_bf16 v[36:39], v[166:169], v[190:193], v[36:39]
	v_mfma_f32_16x16x32_bf16 v[32:35], v[174:177], v[190:193], v[32:35]
	v_mfma_f32_16x16x32_bf16 v[20:23], v[166:169], v[198:201], v[20:23]
	v_mfma_f32_16x16x32_bf16 v[16:19], v[174:177], v[198:201], v[16:19]
	v_mfma_f32_16x16x32_bf16 v[4:7], v[166:169], v[206:209], v[4:7]
	v_mfma_f32_16x16x32_bf16 v[0:3], v[174:177], v[206:209], v[0:3]
	v_mfma_f32_16x16x32_bf16 v[52:55], v[170:173], v[186:189], v[52:55]
	v_mfma_f32_16x16x32_bf16 v[48:51], v[178:181], v[186:189], v[48:51]
	v_mfma_f32_16x16x32_bf16 v[36:39], v[170:173], v[194:197], v[36:39]
	v_mfma_f32_16x16x32_bf16 v[32:35], v[178:181], v[194:197], v[32:35]
	v_mfma_f32_16x16x32_bf16 v[20:23], v[170:173], v[202:205], v[20:23]
	v_mfma_f32_16x16x32_bf16 v[16:19], v[178:181], v[202:205], v[16:19]
	v_mfma_f32_16x16x32_bf16 v[4:7], v[170:173], v[210:213], v[4:7]
	v_mfma_f32_16x16x32_bf16 v[0:3], v[178:181], v[210:213], v[0:3]
	s_barrier
	s_setprio 0
	s_andn2_b64 vcc, exec, s[44:45]
	s_mov_b64 s[46:47], -1
	s_mov_b64 s[44:45], 0
	s_mov_b64 s[48:49], 0x100
	s_cbranch_vccnz .Lkx_744

.Lkx_744:
	s_and_b64 vcc, exec, s[20:21]
	s_cbranch_vccz .LBB0_747
	s_barrier

.LBB0_770:
	s_add_u32 s81, s38, 0x100
	s_addc_u32 s82, s39, 0
	s_mov_b32 s83, -2
	ds_read_b128 v[84:87], v208
	ds_read_b128 v[100:103], v208 offset:1024
	ds_read_b128 v[120:123], v208 offset:2048
	ds_read_b128 v[140:143], v208 offset:3072
	ds_read_b128 v[144:147], v209
	ds_read_b128 v[148:151], v209 offset:1024
	ds_read_b128 v[152:155], v209 offset:2048
	ds_read_b128 v[170:173], v209 offset:3072
	s_add_u32 s6, s8, 0x100
	s_addc_u32 s7, s9, 0
	s_cmp_eq_u32 s83, 2
	s_cselect_b32 s41, s35, s7
	s_cselect_b32 s40, s34, s6
	s_cselect_b32 s39, s37, s82
	s_cselect_b32 s38, s36, s81
	s_add_i32 m0, s42, 0xc000
	ds_read_b128 v[174:177], v210
	ds_read_b128 v[178:181], v210 offset:1024
	ds_read_b128 v[182:185], v210 offset:2048
	ds_read_b128 v[186:189], v210 offset:3072
	ds_read_b128 v[190:193], v210 offset:4096
	ds_read_b128 v[194:197], v210 offset:5120
	ds_read_b128 v[198:201], v210 offset:6144
	ds_read_b128 v[202:205], v210 offset:7168
	global_load_lds_dwordx4 v162, s[8:9]
	s_add_i32 m0, s42, 0xe000
	s_nop 0
	global_load_lds_dwordx4 v164, s[8:9]
	s_waitcnt vmcnt(8)
	s_waitcnt lgkmcnt(0)
	s_setprio 1
	s_barrier
	v_mfma_f32_16x16x32_bf16 v[136:139], v[84:87], v[174:177], 0
	v_mfma_f32_16x16x32_bf16 v[132:135], v[120:123], v[174:177], 0
	v_mfma_f32_16x16x32_bf16 v[116:119], v[84:87], v[182:185], 0
	v_mfma_f32_16x16x32_bf16 v[112:115], v[120:123], v[182:185], 0
	v_mfma_f32_16x16x32_bf16 v[96:99], v[84:87], v[190:193], 0
	v_mfma_f32_16x16x32_bf16 v[92:95], v[120:123], v[190:193], 0
	v_mfma_f32_16x16x32_bf16 v[76:79], v[84:87], v[198:201], 0
	v_mfma_f32_16x16x32_bf16 v[72:75], v[120:123], v[198:201], 0
	v_mfma_f32_16x16x32_bf16 v[136:139], v[100:103], v[178:181], v[136:139]
	v_mfma_f32_16x16x32_bf16 v[132:135], v[140:143], v[178:181], v[132:135]
	v_mfma_f32_16x16x32_bf16 v[116:119], v[100:103], v[186:189], v[116:119]
	v_mfma_f32_16x16x32_bf16 v[112:115], v[140:143], v[186:189], v[112:115]
	v_mfma_f32_16x16x32_bf16 v[96:99], v[100:103], v[194:197], v[96:99]
	v_mfma_f32_16x16x32_bf16 v[92:95], v[140:143], v[194:197], v[92:95]
	v_mfma_f32_16x16x32_bf16 v[76:79], v[100:103], v[202:205], v[76:79]
	v_mfma_f32_16x16x32_bf16 v[72:75], v[140:143], v[202:205], v[72:75]
	v_mfma_f32_16x16x32_bf16 v[128:131], v[144:147], v[174:177], 0
	v_mfma_f32_16x16x32_bf16 v[124:127], v[152:155], v[174:177], 0
	v_mfma_f32_16x16x32_bf16 v[108:111], v[144:147], v[182:185], 0
	v_mfma_f32_16x16x32_bf16 v[104:107], v[152:155], v[182:185], 0
	v_mfma_f32_16x16x32_bf16 v[88:91], v[144:147], v[190:193], 0
	v_mfma_f32_16x16x32_bf16 v[80:83], v[152:155], v[190:193], 0
	v_mfma_f32_16x16x32_bf16 v[68:71], v[144:147], v[198:201], 0
	v_mfma_f32_16x16x32_bf16 v[64:67], v[152:155], v[198:201], 0
	v_mfma_f32_16x16x32_bf16 v[128:131], v[148:151], v[178:181], v[128:131]
	v_mfma_f32_16x16x32_bf16 v[124:127], v[170:173], v[178:181], v[124:127]
	v_mfma_f32_16x16x32_bf16 v[108:111], v[148:151], v[186:189], v[108:111]
	v_mfma_f32_16x16x32_bf16 v[104:107], v[170:173], v[186:189], v[104:107]
	v_mfma_f32_16x16x32_bf16 v[88:91], v[148:151], v[194:197], v[88:91]
	v_mfma_f32_16x16x32_bf16 v[80:83], v[170:173], v[194:197], v[80:83]
	v_mfma_f32_16x16x32_bf16 v[68:71], v[148:151], v[202:205], v[68:71]
	v_mfma_f32_16x16x32_bf16 v[64:67], v[170:173], v[202:205], v[64:67]
	s_barrier
	s_setprio 0
	s_add_i32 s8, s61, s3
	s_add_u32 s98, s38, 0x80
	s_addc_u32 s99, s39, 0
	s_mov_b32 m0, s8
	ds_read_b128 v[174:177], v210 offset:16384
	ds_read_b128 v[178:181], v210 offset:17408
	ds_read_b128 v[182:185], v210 offset:18432
	ds_read_b128 v[186:189], v210 offset:19456
	ds_read_b128 v[190:193], v210 offset:20480
	ds_read_b128 v[194:197], v210 offset:21504
	ds_read_b128 v[198:201], v210 offset:22528
	ds_read_b128 v[202:205], v210 offset:23552
	global_load_lds_dwordx4 v156, s[38:39]
	s_add_i32 m0, s8, 0x2000
	s_add_u32 s8, s38, 0x18000
	s_addc_u32 s9, s39, 0
	s_add_i32 s84, s62, s3
	global_load_lds_dwordx4 v158, s[38:39]
	s_mov_b32 m0, s84
	s_add_u32 s100, s40, 0x80
	s_addc_u32 s101, s41, 0
	global_load_lds_dwordx4 v156, s[8:9]
	s_add_i32 m0, s84, 0x2000
	s_nop 0
	global_load_lds_dwordx4 v158, s[8:9]
	s_mov_b32 m0, s42
	s_nop 0
	global_load_lds_dwordx4 v156, s[40:41]
	s_mov_b32 m0, s43
	s_nop 0
	global_load_lds_dwordx4 v158, s[40:41]
	s_waitcnt vmcnt(8)
	s_waitcnt lgkmcnt(0)
	s_setprio 1
	s_barrier
	v_mfma_f32_16x16x32_bf16 v[60:63], v[84:87], v[174:177], 0
	v_mfma_f32_16x16x32_bf16 v[56:59], v[120:123], v[174:177], 0
	v_mfma_f32_16x16x32_bf16 v[44:47], v[84:87], v[182:185], 0
	v_mfma_f32_16x16x32_bf16 v[40:43], v[120:123], v[182:185], 0
	v_mfma_f32_16x16x32_bf16 v[28:31], v[84:87], v[190:193], 0
	v_mfma_f32_16x16x32_bf16 v[24:27], v[120:123], v[190:193], 0
	v_mfma_f32_16x16x32_bf16 v[12:15], v[84:87], v[198:201], 0
	v_mfma_f32_16x16x32_bf16 v[8:11], v[120:123], v[198:201], 0
	v_mfma_f32_16x16x32_bf16 v[60:63], v[100:103], v[178:181], v[60:63]
	v_mfma_f32_16x16x32_bf16 v[56:59], v[140:143], v[178:181], v[56:59]
	v_mfma_f32_16x16x32_bf16 v[44:47], v[100:103], v[186:189], v[44:47]
	v_mfma_f32_16x16x32_bf16 v[40:43], v[140:143], v[186:189], v[40:43]
	v_mfma_f32_16x16x32_bf16 v[28:31], v[100:103], v[194:197], v[28:31]
	v_mfma_f32_16x16x32_bf16 v[24:27], v[140:143], v[194:197], v[24:27]
	v_mfma_f32_16x16x32_bf16 v[12:15], v[100:103], v[202:205], v[12:15]
	v_mfma_f32_16x16x32_bf16 v[8:11], v[140:143], v[202:205], v[8:11]
	v_mfma_f32_16x16x32_bf16 v[52:55], v[144:147], v[174:177], 0
	v_mfma_f32_16x16x32_bf16 v[48:51], v[152:155], v[174:177], 0
	v_mfma_f32_16x16x32_bf16 v[36:39], v[144:147], v[182:185], 0
	v_mfma_f32_16x16x32_bf16 v[32:35], v[152:155], v[182:185], 0
	v_mfma_f32_16x16x32_bf16 v[20:23], v[144:147], v[190:193], 0
	v_mfma_f32_16x16x32_bf16 v[16:19], v[152:155], v[190:193], 0
	v_mfma_f32_16x16x32_bf16 v[4:7], v[144:147], v[198:201], 0
	v_mfma_f32_16x16x32_bf16 v[0:3], v[152:155], v[198:201], 0
	v_mfma_f32_16x16x32_bf16 v[52:55], v[148:151], v[178:181], v[52:55]
	v_mfma_f32_16x16x32_bf16 v[48:51], v[170:173], v[178:181], v[48:51]
	v_mfma_f32_16x16x32_bf16 v[36:39], v[148:151], v[186:189], v[36:39]
	v_mfma_f32_16x16x32_bf16 v[32:35], v[170:173], v[186:189], v[32:35]
	v_mfma_f32_16x16x32_bf16 v[20:23], v[148:151], v[194:197], v[20:23]
	v_mfma_f32_16x16x32_bf16 v[16:19], v[170:173], v[194:197], v[16:19]
	v_mfma_f32_16x16x32_bf16 v[4:7], v[148:151], v[202:205], v[4:7]
	v_mfma_f32_16x16x32_bf16 v[0:3], v[170:173], v[202:205], v[0:3]
	s_barrier
	s_setprio 0
	s_add_i32 s84, 0, 0x18000
	s_add_i32 s85, 0, 0x1c000
	v_add_u32_e32 v140, s84, v207
	v_add_u32_e32 v160, s85, v207
	ds_read_b128 v[84:87], v140
	ds_read_b128 v[100:103], v140 offset:1024
	ds_read_b128 v[120:123], v140 offset:2048
	ds_read_b128 v[140:143], v140 offset:3072
	ds_read_b128 v[144:147], v160
	ds_read_b128 v[148:151], v160 offset:1024
	ds_read_b128 v[152:155], v160 offset:2048
	ds_read_b128 v[170:173], v160 offset:3072
	s_add_u32 s8, s40, 0x18000
	s_addc_u32 s9, s41, 0
	s_mov_b32 m0, s44
	ds_read_b128 v[174:177], v210 offset:32768
	ds_read_b128 v[178:181], v210 offset:33792
	ds_read_b128 v[182:185], v210 offset:34816
	ds_read_b128 v[186:189], v210 offset:35840
	ds_read_b128 v[190:193], v210 offset:36864
	ds_read_b128 v[194:197], v210 offset:37888
	ds_read_b128 v[198:201], v210 offset:38912
	ds_read_b128 v[202:205], v210 offset:39936
	global_load_lds_dwordx4 v156, s[8:9]
	s_mov_b32 m0, s45
	s_nop 0
	global_load_lds_dwordx4 v158, s[8:9]
	s_waitcnt vmcnt(8)
	s_waitcnt lgkmcnt(0)
	s_setprio 1
	s_barrier
	v_mfma_f32_16x16x32_bf16 v[136:139], v[84:87], v[174:177], v[136:139]
	v_mfma_f32_16x16x32_bf16 v[132:135], v[120:123], v[174:177], v[132:135]
	v_mfma_f32_16x16x32_bf16 v[116:119], v[84:87], v[182:185], v[116:119]
	v_mfma_f32_16x16x32_bf16 v[112:115], v[120:123], v[182:185], v[112:115]
	v_mfma_f32_16x16x32_bf16 v[96:99], v[84:87], v[190:193], v[96:99]
	v_mfma_f32_16x16x32_bf16 v[92:95], v[120:123], v[190:193], v[92:95]
	v_mfma_f32_16x16x32_bf16 v[76:79], v[84:87], v[198:201], v[76:79]
	v_mfma_f32_16x16x32_bf16 v[72:75], v[120:123], v[198:201], v[72:75]
	v_mfma_f32_16x16x32_bf16 v[136:139], v[100:103], v[178:181], v[136:139]
	v_mfma_f32_16x16x32_bf16 v[132:135], v[140:143], v[178:181], v[132:135]
	v_mfma_f32_16x16x32_bf16 v[116:119], v[100:103], v[186:189], v[116:119]
	v_mfma_f32_16x16x32_bf16 v[112:115], v[140:143], v[186:189], v[112:115]
	v_mfma_f32_16x16x32_bf16 v[96:99], v[100:103], v[194:197], v[96:99]
	v_mfma_f32_16x16x32_bf16 v[92:95], v[140:143], v[194:197], v[92:95]
	v_mfma_f32_16x16x32_bf16 v[76:79], v[100:103], v[202:205], v[76:79]
	v_mfma_f32_16x16x32_bf16 v[72:75], v[140:143], v[202:205], v[72:75]
	v_mfma_f32_16x16x32_bf16 v[128:131], v[144:147], v[174:177], v[128:131]
	v_mfma_f32_16x16x32_bf16 v[124:127], v[152:155], v[174:177], v[124:127]
	v_mfma_f32_16x16x32_bf16 v[108:111], v[144:147], v[182:185], v[108:111]
	v_mfma_f32_16x16x32_bf16 v[104:107], v[152:155], v[182:185], v[104:107]
	v_mfma_f32_16x16x32_bf16 v[88:91], v[144:147], v[190:193], v[88:91]
	v_mfma_f32_16x16x32_bf16 v[80:83], v[152:155], v[190:193], v[80:83]
	v_mfma_f32_16x16x32_bf16 v[68:71], v[144:147], v[198:201], v[68:71]
	v_mfma_f32_16x16x32_bf16 v[64:67], v[152:155], v[198:201], v[64:67]
	v_mfma_f32_16x16x32_bf16 v[128:131], v[148:151], v[178:181], v[128:131]
	v_mfma_f32_16x16x32_bf16 v[124:127], v[170:173], v[178:181], v[124:127]
	v_mfma_f32_16x16x32_bf16 v[108:111], v[148:151], v[186:189], v[108:111]
	v_mfma_f32_16x16x32_bf16 v[104:107], v[170:173], v[186:189], v[104:107]
	v_mfma_f32_16x16x32_bf16 v[88:91], v[148:151], v[194:197], v[88:91]
	v_mfma_f32_16x16x32_bf16 v[80:83], v[170:173], v[194:197], v[80:83]
	v_mfma_f32_16x16x32_bf16 v[68:71], v[148:151], v[202:205], v[68:71]
	v_mfma_f32_16x16x32_bf16 v[64:67], v[170:173], v[202:205], v[64:67]
	s_barrier
	s_setprio 0
	s_add_i32 s8, s84, s3
	s_mov_b32 m0, s8
	ds_read_b128 v[174:177], v210 offset:49152
	ds_read_b128 v[178:181], v210 offset:50176
	ds_read_b128 v[182:185], v210 offset:51200
	ds_read_b128 v[186:189], v210 offset:52224
	ds_read_b128 v[190:193], v210 offset:53248
	ds_read_b128 v[194:197], v210 offset:54272
	ds_read_b128 v[198:201], v210 offset:55296
	ds_read_b128 v[202:205], v210 offset:56320
	global_load_lds_dwordx4 v156, s[98:99]
	s_add_i32 m0, s8, 0x2000
	s_add_u32 s8, s38, 0x18080
	s_addc_u32 s9, s39, 0
	s_add_i32 s38, s85, s3
	global_load_lds_dwordx4 v158, s[98:99]
	s_mov_b32 m0, s38
	s_nop 0
	global_load_lds_dwordx4 v156, s[8:9]
	s_add_i32 m0, s38, 0x2000
	s_nop 0
	global_load_lds_dwordx4 v158, s[8:9]
	s_mov_b32 m0, s51
	s_nop 0
	global_load_lds_dwordx4 v156, s[100:101]
	s_mov_b32 m0, s52
	s_nop 0
	global_load_lds_dwordx4 v158, s[100:101]
	s_waitcnt vmcnt(8)
	s_waitcnt lgkmcnt(0)
	s_setprio 1
	s_barrier
	v_mfma_f32_16x16x32_bf16 v[60:63], v[84:87], v[174:177], v[60:63]
	v_mfma_f32_16x16x32_bf16 v[56:59], v[120:123], v[174:177], v[56:59]
	v_mfma_f32_16x16x32_bf16 v[44:47], v[84:87], v[182:185], v[44:47]
	v_mfma_f32_16x16x32_bf16 v[40:43], v[120:123], v[182:185], v[40:43]
	v_mfma_f32_16x16x32_bf16 v[28:31], v[84:87], v[190:193], v[28:31]
	v_mfma_f32_16x16x32_bf16 v[24:27], v[120:123], v[190:193], v[24:27]
	v_mfma_f32_16x16x32_bf16 v[12:15], v[84:87], v[198:201], v[12:15]
	v_mfma_f32_16x16x32_bf16 v[8:11], v[120:123], v[198:201], v[8:11]
	v_mfma_f32_16x16x32_bf16 v[60:63], v[100:103], v[178:181], v[60:63]
	v_mfma_f32_16x16x32_bf16 v[56:59], v[140:143], v[178:181], v[56:59]
	v_mfma_f32_16x16x32_bf16 v[44:47], v[100:103], v[186:189], v[44:47]
	v_mfma_f32_16x16x32_bf16 v[40:43], v[140:143], v[186:189], v[40:43]
	v_mfma_f32_16x16x32_bf16 v[28:31], v[100:103], v[194:197], v[28:31]
	v_mfma_f32_16x16x32_bf16 v[24:27], v[140:143], v[194:197], v[24:27]
	v_mfma_f32_16x16x32_bf16 v[12:15], v[100:103], v[202:205], v[12:15]
	v_mfma_f32_16x16x32_bf16 v[8:11], v[140:143], v[202:205], v[8:11]
	v_mfma_f32_16x16x32_bf16 v[52:55], v[144:147], v[174:177], v[52:55]
	v_mfma_f32_16x16x32_bf16 v[48:51], v[152:155], v[174:177], v[48:51]
	v_mfma_f32_16x16x32_bf16 v[36:39], v[144:147], v[182:185], v[36:39]
	v_mfma_f32_16x16x32_bf16 v[32:35], v[152:155], v[182:185], v[32:35]
	v_mfma_f32_16x16x32_bf16 v[20:23], v[144:147], v[190:193], v[20:23]
	v_mfma_f32_16x16x32_bf16 v[16:19], v[152:155], v[190:193], v[16:19]
	v_mfma_f32_16x16x32_bf16 v[4:7], v[144:147], v[198:201], v[4:7]
	v_mfma_f32_16x16x32_bf16 v[0:3], v[152:155], v[198:201], v[0:3]
	v_mfma_f32_16x16x32_bf16 v[52:55], v[148:151], v[178:181], v[52:55]
	v_mfma_f32_16x16x32_bf16 v[48:51], v[170:173], v[178:181], v[48:51]
	v_mfma_f32_16x16x32_bf16 v[36:39], v[148:151], v[186:189], v[36:39]
	v_mfma_f32_16x16x32_bf16 v[32:35], v[170:173], v[186:189], v[32:35]
	v_mfma_f32_16x16x32_bf16 v[20:23], v[148:151], v[194:197], v[20:23]
	v_mfma_f32_16x16x32_bf16 v[16:19], v[170:173], v[194:197], v[16:19]
	v_mfma_f32_16x16x32_bf16 v[4:7], v[148:151], v[202:205], v[4:7]
	v_mfma_f32_16x16x32_bf16 v[0:3], v[170:173], v[202:205], v[0:3]
	s_barrier
	s_setprio 0
	s_add_i32 s83, s83, 2
	s_add_u32 s81, s81, 0x100
	s_addc_u32 s82, s82, 0
	s_cmp_gt_u32 s83, 3
	s_mov_b64 s[8:9], s[6:7]
	s_cbranch_scc1 .Lkx_771

.Lkx_771:
	s_and_b64 vcc, exec, s[30:31]
	s_cbranch_vccz .LBB0_774
	s_barrier

.LBB0_937:
	s_ashr_i32 s27, s26, 31
	s_lshl_b64 s[28:29], s[26:27], 18
	s_add_u32 s28, s3, s28
	s_addc_u32 s29, s44, s29
	s_and_b64 s[30:31], s[4:5], exec
	s_cselect_b32 s9, s29, s7
	s_cselect_b32 s27, s28, s6
	s_ashr_i32 s23, s22, 31
	s_lshl_b64 s[30:31], s[22:23], 18
	s_add_u32 s30, s45, s30
	s_addc_u32 s31, s46, s31
	s_and_b64 s[38:39], s[4:5], exec
	s_cselect_b32 s23, s31, s37
	s_cselect_b32 s35, s30, s36
	s_add_u32 s6, s6, 0x20080
	s_addc_u32 s7, s7, 0
	s_add_u32 s40, s36, 0x100
	s_addc_u32 s41, s37, 0
	s_mov_b32 s42, -2
	ds_read_b128 v[128:131], v175
	ds_read_b128 v[132:135], v175 offset:1024
	ds_read_b128 v[136:139], v175 offset:2048
	ds_read_b128 v[140:143], v175 offset:3072
	ds_read_b128 v[144:147], v176
	ds_read_b128 v[148:151], v176 offset:1024
	ds_read_b128 v[168:171], v176 offset:2048
	ds_read_b128 v[182:185], v176 offset:3072
	s_add_u32 s36, s6, 0xfffe0080
	s_addc_u32 s37, s7, -1
	s_cmp_eq_u32 s42, 4
	s_cselect_b32 s39, s9, s37
	s_cselect_b32 s38, s27, s36
	s_cselect_b32 s37, s23, s41
	s_cselect_b32 s36, s35, s40
	s_add_i32 m0, s48, 0xc000
	ds_read_b128 v[186:189], v177
	ds_read_b128 v[190:193], v177 offset:1024
	ds_read_b128 v[194:197], v177 offset:2048
	ds_read_b128 v[198:201], v177 offset:3072
	ds_read_b128 v[202:205], v177 offset:4096
	ds_read_b128 v[206:209], v177 offset:5120
	ds_read_b128 v[210:213], v177 offset:6144
	ds_read_b128 v[214:217], v177 offset:7168
	global_load_lds_dwordx4 v158, s[6:7]
	s_add_i32 m0, s48, 0xe000
	s_nop 0
	global_load_lds_dwordx4 v160, s[6:7]
	s_waitcnt vmcnt(8)
	s_waitcnt lgkmcnt(0)
	s_setprio 1
	s_barrier
	v_mfma_f32_16x16x32_bf16 v[124:127], v[128:131], v[186:189], 0
	v_mfma_f32_16x16x32_bf16 v[120:123], v[136:139], v[186:189], 0
	v_mfma_f32_16x16x32_bf16 v[112:115], v[128:131], v[194:197], 0
	v_mfma_f32_16x16x32_bf16 v[116:119], v[136:139], v[194:197], 0
	v_mfma_f32_16x16x32_bf16 v[96:99], v[128:131], v[202:205], 0
	v_mfma_f32_16x16x32_bf16 v[104:107], v[136:139], v[202:205], 0
	v_mfma_f32_16x16x32_bf16 v[76:79], v[128:131], v[210:213], 0
	v_mfma_f32_16x16x32_bf16 v[72:75], v[136:139], v[210:213], 0
	v_mfma_f32_16x16x32_bf16 v[124:127], v[132:135], v[190:193], v[124:127]
	v_mfma_f32_16x16x32_bf16 v[120:123], v[140:143], v[190:193], v[120:123]
	v_mfma_f32_16x16x32_bf16 v[112:115], v[132:135], v[198:201], v[112:115]
	v_mfma_f32_16x16x32_bf16 v[116:119], v[140:143], v[198:201], v[116:119]
	v_mfma_f32_16x16x32_bf16 v[96:99], v[132:135], v[206:209], v[96:99]
	v_mfma_f32_16x16x32_bf16 v[104:107], v[140:143], v[206:209], v[104:107]
	v_mfma_f32_16x16x32_bf16 v[76:79], v[132:135], v[214:217], v[76:79]
	v_mfma_f32_16x16x32_bf16 v[72:75], v[140:143], v[214:217], v[72:75]
	v_mfma_f32_16x16x32_bf16 v[108:111], v[144:147], v[186:189], 0
	v_mfma_f32_16x16x32_bf16 v[100:103], v[168:171], v[186:189], 0
	v_mfma_f32_16x16x32_bf16 v[88:91], v[144:147], v[194:197], 0
	v_mfma_f32_16x16x32_bf16 v[92:95], v[168:171], v[194:197], 0
	v_mfma_f32_16x16x32_bf16 v[84:87], v[144:147], v[202:205], 0
	v_mfma_f32_16x16x32_bf16 v[80:83], v[168:171], v[202:205], 0
	v_mfma_f32_16x16x32_bf16 v[68:71], v[144:147], v[210:213], 0
	v_mfma_f32_16x16x32_bf16 v[64:67], v[168:171], v[210:213], 0
	v_mfma_f32_16x16x32_bf16 v[108:111], v[148:151], v[190:193], v[108:111]
	v_mfma_f32_16x16x32_bf16 v[100:103], v[182:185], v[190:193], v[100:103]
	v_mfma_f32_16x16x32_bf16 v[88:91], v[148:151], v[198:201], v[88:91]
	v_mfma_f32_16x16x32_bf16 v[92:95], v[182:185], v[198:201], v[92:95]
	v_mfma_f32_16x16x32_bf16 v[84:87], v[148:151], v[206:209], v[84:87]
	v_mfma_f32_16x16x32_bf16 v[80:83], v[182:185], v[206:209], v[80:83]
	v_mfma_f32_16x16x32_bf16 v[68:71], v[148:151], v[214:217], v[68:71]
	v_mfma_f32_16x16x32_bf16 v[64:67], v[182:185], v[214:217], v[64:67]
	s_barrier
	s_setprio 0
	s_add_i32 s43, s72, s47
	s_add_u32 s98, s36, 0x80
	s_addc_u32 s99, s37, 0
	s_mov_b32 m0, s43
	ds_read_b128 v[186:189], v177 offset:16384
	ds_read_b128 v[190:193], v177 offset:17408
	ds_read_b128 v[194:197], v177 offset:18432
	ds_read_b128 v[198:201], v177 offset:19456
	ds_read_b128 v[202:205], v177 offset:20480
	ds_read_b128 v[206:209], v177 offset:21504
	ds_read_b128 v[210:213], v177 offset:22528
	ds_read_b128 v[214:217], v177 offset:23552
	global_load_lds_dwordx4 v152, s[36:37]
	s_add_i32 m0, s43, 0x2000
	s_add_u32 s88, s36, 0x20000
	s_addc_u32 s89, s37, 0
	s_add_i32 s43, s73, s47
	global_load_lds_dwordx4 v154, s[36:37]
	s_mov_b32 m0, s43
	s_add_u32 s100, s38, 0x80
	s_addc_u32 s101, s39, 0
	global_load_lds_dwordx4 v152, s[88:89]
	s_add_i32 m0, s43, 0x2000
	s_nop 0
	global_load_lds_dwordx4 v154, s[88:89]
	s_mov_b32 m0, s48
	s_nop 0
	global_load_lds_dwordx4 v152, s[38:39]
	s_mov_b32 m0, s49
	s_nop 0
	global_load_lds_dwordx4 v154, s[38:39]
	s_waitcnt vmcnt(8)
	s_waitcnt lgkmcnt(0)
	s_setprio 1
	s_barrier
	v_mfma_f32_16x16x32_bf16 v[60:63], v[128:131], v[186:189], 0
	v_mfma_f32_16x16x32_bf16 v[56:59], v[136:139], v[186:189], 0
	v_mfma_f32_16x16x32_bf16 v[44:47], v[128:131], v[194:197], 0
	v_mfma_f32_16x16x32_bf16 v[40:43], v[136:139], v[194:197], 0
	v_mfma_f32_16x16x32_bf16 v[28:31], v[128:131], v[202:205], 0
	v_mfma_f32_16x16x32_bf16 v[24:27], v[136:139], v[202:205], 0
	v_mfma_f32_16x16x32_bf16 v[12:15], v[128:131], v[210:213], 0
	v_mfma_f32_16x16x32_bf16 v[8:11], v[136:139], v[210:213], 0
	v_mfma_f32_16x16x32_bf16 v[60:63], v[132:135], v[190:193], v[60:63]
	v_mfma_f32_16x16x32_bf16 v[56:59], v[140:143], v[190:193], v[56:59]
	v_mfma_f32_16x16x32_bf16 v[44:47], v[132:135], v[198:201], v[44:47]
	v_mfma_f32_16x16x32_bf16 v[40:43], v[140:143], v[198:201], v[40:43]
	v_mfma_f32_16x16x32_bf16 v[28:31], v[132:135], v[206:209], v[28:31]
	v_mfma_f32_16x16x32_bf16 v[24:27], v[140:143], v[206:209], v[24:27]
	v_mfma_f32_16x16x32_bf16 v[12:15], v[132:135], v[214:217], v[12:15]
	v_mfma_f32_16x16x32_bf16 v[8:11], v[140:143], v[214:217], v[8:11]
	v_mfma_f32_16x16x32_bf16 v[52:55], v[144:147], v[186:189], 0
	v_mfma_f32_16x16x32_bf16 v[48:51], v[168:171], v[186:189], 0
	v_mfma_f32_16x16x32_bf16 v[36:39], v[144:147], v[194:197], 0
	v_mfma_f32_16x16x32_bf16 v[32:35], v[168:171], v[194:197], 0
	v_mfma_f32_16x16x32_bf16 v[20:23], v[144:147], v[202:205], 0
	v_mfma_f32_16x16x32_bf16 v[16:19], v[168:171], v[202:205], 0
	v_mfma_f32_16x16x32_bf16 v[4:7], v[144:147], v[210:213], 0
	v_mfma_f32_16x16x32_bf16 v[0:3], v[168:171], v[210:213], 0
	v_mfma_f32_16x16x32_bf16 v[52:55], v[148:151], v[190:193], v[52:55]
	v_mfma_f32_16x16x32_bf16 v[48:51], v[182:185], v[190:193], v[48:51]
	v_mfma_f32_16x16x32_bf16 v[36:39], v[148:151], v[198:201], v[36:39]
	v_mfma_f32_16x16x32_bf16 v[32:35], v[182:185], v[198:201], v[32:35]
	v_mfma_f32_16x16x32_bf16 v[20:23], v[148:151], v[206:209], v[20:23]
	v_mfma_f32_16x16x32_bf16 v[16:19], v[182:185], v[206:209], v[16:19]
	v_mfma_f32_16x16x32_bf16 v[4:7], v[148:151], v[214:217], v[4:7]
	v_mfma_f32_16x16x32_bf16 v[0:3], v[182:185], v[214:217], v[0:3]
	s_barrier
	s_setprio 0
	s_add_i32 s43, 0, 0x18000
	s_add_i32 s88, 0, 0x1c000
	v_add_u32_e32 v140, s43, v173
	v_add_u32_e32 v156, s88, v173
	ds_read_b128 v[128:131], v140
	ds_read_b128 v[132:135], v140 offset:1024
	ds_read_b128 v[136:139], v140 offset:2048
	ds_read_b128 v[140:143], v140 offset:3072
	ds_read_b128 v[144:147], v156
	ds_read_b128 v[148:151], v156 offset:1024
	ds_read_b128 v[168:171], v156 offset:2048
	ds_read_b128 v[182:185], v156 offset:3072
	s_add_u32 s38, s38, 0x20000
	s_addc_u32 s39, s39, 0
	s_mov_b32 m0, s50
	ds_read_b128 v[186:189], v177 offset:32768
	ds_read_b128 v[190:193], v177 offset:33792
	ds_read_b128 v[194:197], v177 offset:34816
	ds_read_b128 v[198:201], v177 offset:35840
	ds_read_b128 v[202:205], v177 offset:36864
	ds_read_b128 v[206:209], v177 offset:37888
	ds_read_b128 v[210:213], v177 offset:38912
	ds_read_b128 v[214:217], v177 offset:39936
	global_load_lds_dwordx4 v152, s[38:39]
	s_mov_b32 m0, s51
	s_nop 0
	global_load_lds_dwordx4 v154, s[38:39]
	s_waitcnt vmcnt(8)
	s_waitcnt lgkmcnt(0)
	s_setprio 1
	s_barrier
	v_mfma_f32_16x16x32_bf16 v[124:127], v[128:131], v[186:189], v[124:127]
	v_mfma_f32_16x16x32_bf16 v[120:123], v[136:139], v[186:189], v[120:123]
	v_mfma_f32_16x16x32_bf16 v[112:115], v[128:131], v[194:197], v[112:115]
	v_mfma_f32_16x16x32_bf16 v[116:119], v[136:139], v[194:197], v[116:119]
	v_mfma_f32_16x16x32_bf16 v[96:99], v[128:131], v[202:205], v[96:99]
	v_mfma_f32_16x16x32_bf16 v[104:107], v[136:139], v[202:205], v[104:107]
	v_mfma_f32_16x16x32_bf16 v[76:79], v[128:131], v[210:213], v[76:79]
	v_mfma_f32_16x16x32_bf16 v[72:75], v[136:139], v[210:213], v[72:75]
	v_mfma_f32_16x16x32_bf16 v[124:127], v[132:135], v[190:193], v[124:127]
	v_mfma_f32_16x16x32_bf16 v[120:123], v[140:143], v[190:193], v[120:123]
	v_mfma_f32_16x16x32_bf16 v[112:115], v[132:135], v[198:201], v[112:115]
	v_mfma_f32_16x16x32_bf16 v[116:119], v[140:143], v[198:201], v[116:119]
	v_mfma_f32_16x16x32_bf16 v[96:99], v[132:135], v[206:209], v[96:99]
	v_mfma_f32_16x16x32_bf16 v[104:107], v[140:143], v[206:209], v[104:107]
	v_mfma_f32_16x16x32_bf16 v[76:79], v[132:135], v[214:217], v[76:79]
	v_mfma_f32_16x16x32_bf16 v[72:75], v[140:143], v[214:217], v[72:75]
	v_mfma_f32_16x16x32_bf16 v[108:111], v[144:147], v[186:189], v[108:111]
	v_mfma_f32_16x16x32_bf16 v[100:103], v[168:171], v[186:189], v[100:103]
	v_mfma_f32_16x16x32_bf16 v[88:91], v[144:147], v[194:197], v[88:91]
	v_mfma_f32_16x16x32_bf16 v[92:95], v[168:171], v[194:197], v[92:95]
	v_mfma_f32_16x16x32_bf16 v[84:87], v[144:147], v[202:205], v[84:87]
	v_mfma_f32_16x16x32_bf16 v[80:83], v[168:171], v[202:205], v[80:83]
	v_mfma_f32_16x16x32_bf16 v[68:71], v[144:147], v[210:213], v[68:71]
	v_mfma_f32_16x16x32_bf16 v[64:67], v[168:171], v[210:213], v[64:67]
	v_mfma_f32_16x16x32_bf16 v[108:111], v[148:151], v[190:193], v[108:111]
	v_mfma_f32_16x16x32_bf16 v[100:103], v[182:185], v[190:193], v[100:103]
	v_mfma_f32_16x16x32_bf16 v[88:91], v[148:151], v[198:201], v[88:91]
	v_mfma_f32_16x16x32_bf16 v[92:95], v[182:185], v[198:201], v[92:95]
	v_mfma_f32_16x16x32_bf16 v[84:87], v[148:151], v[206:209], v[84:87]
	v_mfma_f32_16x16x32_bf16 v[80:83], v[182:185], v[206:209], v[80:83]
	v_mfma_f32_16x16x32_bf16 v[68:71], v[148:151], v[214:217], v[68:71]
	v_mfma_f32_16x16x32_bf16 v[64:67], v[182:185], v[214:217], v[64:67]
	s_barrier
	s_setprio 0
	s_add_i32 s38, s43, s47
	s_mov_b32 m0, s38
	ds_read_b128 v[186:189], v177 offset:49152
	ds_read_b128 v[190:193], v177 offset:50176
	ds_read_b128 v[194:197], v177 offset:51200
	ds_read_b128 v[198:201], v177 offset:52224
	ds_read_b128 v[202:205], v177 offset:53248
	ds_read_b128 v[206:209], v177 offset:54272
	ds_read_b128 v[210:213], v177 offset:55296
	ds_read_b128 v[214:217], v177 offset:56320
	global_load_lds_dwordx4 v152, s[98:99]
	s_add_i32 m0, s38, 0x2000
	s_add_u32 s36, s36, 0x20080
	s_addc_u32 s37, s37, 0
	s_add_i32 s38, s88, s47
	global_load_lds_dwordx4 v154, s[98:99]
	s_mov_b32 m0, s38
	s_nop 0
	global_load_lds_dwordx4 v152, s[36:37]
	s_add_i32 m0, s38, 0x2000
	s_nop 0
	global_load_lds_dwordx4 v154, s[36:37]
	s_mov_b32 m0, s61
	s_nop 0
	global_load_lds_dwordx4 v152, s[100:101]
	s_mov_b32 m0, s62
	s_nop 0
	global_load_lds_dwordx4 v154, s[100:101]
	s_waitcnt vmcnt(8)
	s_waitcnt lgkmcnt(0)
	s_setprio 1
	s_barrier
	v_mfma_f32_16x16x32_bf16 v[60:63], v[128:131], v[186:189], v[60:63]
	v_mfma_f32_16x16x32_bf16 v[56:59], v[136:139], v[186:189], v[56:59]
	v_mfma_f32_16x16x32_bf16 v[44:47], v[128:131], v[194:197], v[44:47]
	v_mfma_f32_16x16x32_bf16 v[40:43], v[136:139], v[194:197], v[40:43]
	v_mfma_f32_16x16x32_bf16 v[28:31], v[128:131], v[202:205], v[28:31]
	v_mfma_f32_16x16x32_bf16 v[24:27], v[136:139], v[202:205], v[24:27]
	v_mfma_f32_16x16x32_bf16 v[12:15], v[128:131], v[210:213], v[12:15]
	v_mfma_f32_16x16x32_bf16 v[8:11], v[136:139], v[210:213], v[8:11]
	v_mfma_f32_16x16x32_bf16 v[60:63], v[132:135], v[190:193], v[60:63]
	v_mfma_f32_16x16x32_bf16 v[56:59], v[140:143], v[190:193], v[56:59]
	v_mfma_f32_16x16x32_bf16 v[44:47], v[132:135], v[198:201], v[44:47]
	v_mfma_f32_16x16x32_bf16 v[40:43], v[140:143], v[198:201], v[40:43]
	v_mfma_f32_16x16x32_bf16 v[28:31], v[132:135], v[206:209], v[28:31]
	v_mfma_f32_16x16x32_bf16 v[24:27], v[140:143], v[206:209], v[24:27]
	v_mfma_f32_16x16x32_bf16 v[12:15], v[132:135], v[214:217], v[12:15]
	v_mfma_f32_16x16x32_bf16 v[8:11], v[140:143], v[214:217], v[8:11]
	v_mfma_f32_16x16x32_bf16 v[52:55], v[144:147], v[186:189], v[52:55]
	v_mfma_f32_16x16x32_bf16 v[48:51], v[168:171], v[186:189], v[48:51]
	v_mfma_f32_16x16x32_bf16 v[36:39], v[144:147], v[194:197], v[36:39]
	v_mfma_f32_16x16x32_bf16 v[32:35], v[168:171], v[194:197], v[32:35]
	v_mfma_f32_16x16x32_bf16 v[20:23], v[144:147], v[202:205], v[20:23]
	v_mfma_f32_16x16x32_bf16 v[16:19], v[168:171], v[202:205], v[16:19]
	v_mfma_f32_16x16x32_bf16 v[4:7], v[144:147], v[210:213], v[4:7]
	v_mfma_f32_16x16x32_bf16 v[0:3], v[168:171], v[210:213], v[0:3]
	v_mfma_f32_16x16x32_bf16 v[52:55], v[148:151], v[190:193], v[52:55]
	v_mfma_f32_16x16x32_bf16 v[48:51], v[182:185], v[190:193], v[48:51]
	v_mfma_f32_16x16x32_bf16 v[36:39], v[148:151], v[198:201], v[36:39]
	v_mfma_f32_16x16x32_bf16 v[32:35], v[182:185], v[198:201], v[32:35]
	v_mfma_f32_16x16x32_bf16 v[20:23], v[148:151], v[206:209], v[20:23]
	v_mfma_f32_16x16x32_bf16 v[16:19], v[182:185], v[206:209], v[16:19]
	v_mfma_f32_16x16x32_bf16 v[4:7], v[148:151], v[214:217], v[4:7]
	v_mfma_f32_16x16x32_bf16 v[0:3], v[182:185], v[214:217], v[0:3]
	s_barrier
	s_setprio 0
	s_add_i32 s42, s42, 2
	s_add_u32 s6, s6, 0x100
	s_addc_u32 s7, s7, 0
	s_add_u32 s40, s40, 0x100
	s_addc_u32 s41, s41, 0
	s_cmp_gt_u32 s42, 5
	s_cbranch_scc1 .Lkx_938

.Lkx_938:
	s_and_b64 vcc, exec, s[18:19]
	s_cbranch_vccz .LBB0_941
	s_barrier
